# rope epilogue: issue previous group's row stores right after the table/readback wait instead of after the rope math
# baseline (speedup 1.0000x reference)
;     __device__ __forceinline__ void operator()(const f32x4 (&acc)[2][2][4][2], const Unit& u, int wr, int wc, int fr, int fq, PG8_LAS float* stash, int par, PG8_LAS unsigned char* stg, const Unit& un) const {
;     ...
;                     for (int i = 0; i < 4; ++i) { v[i] = acc[ai][bj][m][0][i] * rs; v[4 + i] = acc[ai][bj][m][1][i] * rs; }
;                     if (kind <= 1 && bj == 0) {
;                         const f32x4 c0 = *(const f32x4*)(cs + pos * 16), c1 = *(const f32x4*)(cs + pos * 16 + 4), s0 = *(const f32x4*)(cs + pos * 16 + 8), s1 = *(const f32x4*)(cs + pos * 16 + 12);
; #pragma unroll
;                         for (int i = 0; i < 8; ++i) {
;                             const float c = i < 4 ? c0[i & 3] : c1[i & 3], s = i < 4 ? s0[i & 3] : s1[i & 3];
;                             const float pr = peer_x16(v[i], fq);
;                             const float r = (fq == 0) ? (v[i] * c - pr * s) : (v[i] * c + pr * s);
;                             v[i] = (fq < 2) ? r : v[i];
;                         }
;                     }
;                     if (kind == 0) {
; #pragma unroll
;                         for (int i = 0; i < 8; ++i) v[i] *= C2Q;
;                     }
;                     { u32x4 w; w.x = cvt_pk_bf16(v[0], v[1]); w.y = cvt_pk_bf16(v[2], v[3]); w.z = cvt_pk_bf16(v[4], v[5]); w.w = cvt_pk_bf16(v[6], v[7]);
;                       *(PG8_LAS u32x4*)(stg + fr * 144 + fq * 16 + bj * 64) = w; }
;                 }
;                 {
;                     int kind;
;                     if (odd) kind = (u.pn < 6) ? 0 : (u.pn == 6 ? 1 : 2);
;                     else     kind = (u.pn < 2) ? 0 : (u.pn == 2 ? (wc < 2 ? 1 : 2) : 3);
; #pragma unroll
;                     for (int i = 0; i < 2; ++i) { const int c = fq * 16 + fr + 64 * i, rr = c >> 3, pc = c & 7;
;                         const u32x4 w = *(const PG8_LAS u32x4*)(stg + rr * 144 + pc * 16);
;                         const int rowc = row - fr + rr, posc = rowc & 4095;
;                         if (kind == 1 || kind == 2) {
;                             bf16_t* dst = (kind == 1) ? kd : vt;
;                             if (odd) *(u32x4*)(dst + (size_t)(b * 4 + wc) * (4096 * 64) + (size_t)((posc & 15) * 256 + (posc >> 4)) * 64 + pc * 8) = w;
;                             else     *(u32x4*)(dst + (size_t)(b * 2 + (wc & 1)) * (4096 * 64) + (size_t)posc * 64 + pc * 8) = w;
.Lipe_Q:
	v_mbcnt_lo_u32_b32 v166, -1, 0
	v_mbcnt_hi_u32_b32 v166, -1, v166
	v_readfirstlane_b32 s65, v180
	v_lshrrev_b32_e32 v167, 2, v166
	v_mul_u32_u24_e32 v167, 0x50, v167
	v_and_b32_e32 v168, 3, v166
	v_lshl_add_u32 v167, v168, 4, v167
	v_add_u32_e32 v167, s65, v167
	v_mul_u32_u24_e32 v168, 0x50, v141
	v_add_u32_e32 v168, s65, v168
	v_lshlrev_b32_e32 v166, 4, v166
	s_add_i32 s44, s19, 0
	s_and_b32 s44, s44, 0xfff
	s_lshl_b32 s44, s44, 6
	s_add_u32 s44, s62, s44
	s_addc_u32 s45, s63, 0
	global_load_dwordx4 v[154:157], v166, s[44:45]
	s_add_i32 s44, s19, 16
	s_and_b32 s44, s44, 0xfff
	s_lshl_b32 s44, s44, 6
	s_add_u32 s44, s62, s44
	s_addc_u32 s45, s63, 0
	global_load_dwordx4 v[158:161], v166, s[44:45]
	s_waitcnt vmcnt(1)
	ds_write_b128 v167, v[154:157]
	ds_read_b128 v[218:221], v168
	ds_read_b128 v[222:225], v168 offset:16
	ds_read_b128 v[226:229], v168 offset:32
	ds_read_b128 v[230:233], v168 offset:48
	v_pk_mul_f32 v[118:119], v[118:119], v[152:153] op_sel_hi:[1,0]
	v_pk_mul_f32 v[120:121], v[120:121], v[152:153] op_sel_hi:[1,0]
	v_pk_mul_f32 v[114:115], v[114:115], v[152:153] op_sel_hi:[1,0]
	v_pk_mul_f32 v[116:117], v[116:117], v[152:153] op_sel_hi:[1,0]
	v_pk_mul_f32 v[118:119], v[118:119], s[30:31] op_sel_hi:[1,0]
	v_pk_mul_f32 v[120:121], v[120:121], s[30:31] op_sel_hi:[1,0]
	v_pk_mul_f32 v[114:115], v[114:115], s[30:31] op_sel_hi:[1,0]
	v_pk_mul_f32 v[116:117], v[116:117], s[30:31] op_sel_hi:[1,0]
	v_cvt_pk_bf16_f32 v118, v118, v119
	v_cvt_pk_bf16_f32 v119, v120, v121
	v_cvt_pk_bf16_f32 v120, v114, v115
	v_cvt_pk_bf16_f32 v121, v116, v117
	v_pk_mul_f32 v[126:127], v[126:127], v[152:153] op_sel_hi:[1,0]
	v_pk_mul_f32 v[128:129], v[128:129], v[152:153] op_sel_hi:[1,0]
	v_pk_mul_f32 v[122:123], v[122:123], v[152:153] op_sel_hi:[1,0]
	v_pk_mul_f32 v[124:125], v[124:125], v[152:153] op_sel_hi:[1,0]
	ds_swizzle_b32 v114, v126 offset:0x401f
	ds_swizzle_b32 v115, v127 offset:0x401f
	ds_swizzle_b32 v116, v128 offset:0x401f
	ds_swizzle_b32 v117, v129 offset:0x401f
	ds_swizzle_b32 v162, v122 offset:0x401f
	ds_swizzle_b32 v163, v123 offset:0x401f
	ds_swizzle_b32 v164, v124 offset:0x401f
	ds_swizzle_b32 v165, v125 offset:0x401f
	s_waitcnt lgkmcnt(8)
	v_xor_b32_e32 v226, v201, v226
	v_xor_b32_e32 v227, v201, v227
	v_xor_b32_e32 v228, v201, v228
	v_xor_b32_e32 v229, v201, v229
	v_xor_b32_e32 v230, v201, v230
	v_xor_b32_e32 v231, v201, v231
	v_xor_b32_e32 v232, v201, v232
	v_xor_b32_e32 v233, v201, v233
	s_waitcnt lgkmcnt(4)
	v_mul_f32_e32 v114, v226, v114
	v_fmac_f32_e32 v114, v126, v218
	v_cndmask_b32_e64 v126, v126, v114, s[38:39]
	v_mul_f32_e32 v115, v227, v115
	v_fmac_f32_e32 v115, v127, v219
	v_cndmask_b32_e64 v127, v127, v115, s[38:39]
	v_mul_f32_e32 v116, v228, v116
	v_fmac_f32_e32 v116, v128, v220
	v_cndmask_b32_e64 v128, v128, v116, s[38:39]
	v_mul_f32_e32 v117, v229, v117
	v_fmac_f32_e32 v117, v129, v221
	v_cndmask_b32_e64 v129, v129, v117, s[38:39]
	s_waitcnt lgkmcnt(0)
	v_mul_f32_e32 v162, v230, v162
	v_fmac_f32_e32 v162, v122, v222
	v_cndmask_b32_e64 v122, v122, v162, s[38:39]
	v_mul_f32_e32 v163, v231, v163
	v_fmac_f32_e32 v163, v123, v223
	v_cndmask_b32_e64 v123, v123, v163, s[38:39]
	v_mul_f32_e32 v164, v232, v164
	v_fmac_f32_e32 v164, v124, v224
	v_cndmask_b32_e64 v124, v124, v164, s[38:39]
	v_mul_f32_e32 v165, v233, v165
	v_fmac_f32_e32 v165, v125, v225
	v_cndmask_b32_e64 v125, v125, v165, s[38:39]
	v_pk_mul_f32 v[126:127], v[126:127], s[30:31] op_sel_hi:[1,0]
	v_pk_mul_f32 v[128:129], v[128:129], s[30:31] op_sel_hi:[1,0]
	v_pk_mul_f32 v[122:123], v[122:123], s[30:31] op_sel_hi:[1,0]
	v_pk_mul_f32 v[124:125], v[124:125], s[30:31] op_sel_hi:[1,0]
	v_cvt_pk_bf16_f32 v126, v126, v127
	v_cvt_pk_bf16_f32 v127, v128, v129
	v_cvt_pk_bf16_f32 v128, v122, v123
	v_cvt_pk_bf16_f32 v129, v124, v125
	ds_write_b128 v178, v[126:129]
	ds_write_b128 v178, v[118:121] offset:64
	ds_read_b128 v[122:125], v180
	ds_read_b128 v[114:117], v180 offset:1152
	s_add_i32 s44, s19, 32
	s_and_b32 s44, s44, 0xfff
	s_lshl_b32 s44, s44, 6
	s_add_u32 s44, s62, s44
	s_addc_u32 s45, s63, 0
	global_load_dwordx4 v[154:157], v166, s[44:45]
	s_waitcnt vmcnt(1)
	ds_write_b128 v167, v[158:161]
	ds_read_b128 v[218:221], v168
	ds_read_b128 v[222:225], v168 offset:16
	ds_read_b128 v[226:229], v168 offset:32
	ds_read_b128 v[230:233], v168 offset:48
	v_pk_mul_f32 v[102:103], v[102:103], v[152:153] op_sel:[0,1]
	v_pk_mul_f32 v[104:105], v[104:105], v[152:153] op_sel:[0,1]
	v_pk_mul_f32 v[98:99], v[98:99], v[152:153] op_sel:[0,1]
	v_pk_mul_f32 v[100:101], v[100:101], v[152:153] op_sel:[0,1]
	v_pk_mul_f32 v[102:103], v[102:103], s[30:31] op_sel_hi:[1,0]
	v_pk_mul_f32 v[104:105], v[104:105], s[30:31] op_sel_hi:[1,0]
	v_pk_mul_f32 v[98:99], v[98:99], s[30:31] op_sel_hi:[1,0]
	v_pk_mul_f32 v[100:101], v[100:101], s[30:31] op_sel_hi:[1,0]
	v_cvt_pk_bf16_f32 v102, v102, v103
	v_cvt_pk_bf16_f32 v103, v104, v105
	v_cvt_pk_bf16_f32 v104, v98, v99
	v_cvt_pk_bf16_f32 v105, v100, v101
	v_pk_mul_f32 v[110:111], v[110:111], v[152:153] op_sel:[0,1]
	v_pk_mul_f32 v[112:113], v[112:113], v[152:153] op_sel:[0,1]
	v_pk_mul_f32 v[106:107], v[106:107], v[152:153] op_sel:[0,1]
	v_pk_mul_f32 v[108:109], v[108:109], v[152:153] op_sel:[0,1]
	ds_swizzle_b32 v98, v110 offset:0x401f
	ds_swizzle_b32 v99, v111 offset:0x401f
	ds_swizzle_b32 v100, v112 offset:0x401f
	ds_swizzle_b32 v101, v113 offset:0x401f
	ds_swizzle_b32 v162, v106 offset:0x401f
	ds_swizzle_b32 v163, v107 offset:0x401f
	ds_swizzle_b32 v164, v108 offset:0x401f
	ds_swizzle_b32 v165, v109 offset:0x401f
	s_waitcnt lgkmcnt(8)
;     __device__ __forceinline__ void operator()(const f32x4 (&acc)[2][2][4][2], const Unit& u, int wr, int wc, int fr, int fq, PG8_LAS float* stash, int par, PG8_LAS unsigned char* stg, const Unit& un) const {
;     ...
;                     for (int i = 0; i < 4; ++i) { v[i] = acc[ai][bj][m][0][i] * rs; v[4 + i] = acc[ai][bj][m][1][i] * rs; }
;                     if (kind <= 1 && bj == 0) {
;                         const f32x4 c0 = *(const f32x4*)(cs + pos * 16), c1 = *(const f32x4*)(cs + pos * 16 + 4), s0 = *(const f32x4*)(cs + pos * 16 + 8), s1 = *(const f32x4*)(cs + pos * 16 + 12);
; #pragma unroll
;                         for (int i = 0; i < 8; ++i) {
;                             const float c = i < 4 ? c0[i & 3] : c1[i & 3], s = i < 4 ? s0[i & 3] : s1[i & 3];
;                             const float pr = peer_x16(v[i], fq);
;                             const float r = (fq == 0) ? (v[i] * c - pr * s) : (v[i] * c + pr * s);
;                             v[i] = (fq < 2) ? r : v[i];
;                         }
;                     }
;                     if (kind == 0) {
; #pragma unroll
;                         for (int i = 0; i < 8; ++i) v[i] *= C2Q;
;                     }
;                     { u32x4 w; w.x = cvt_pk_bf16(v[0], v[1]); w.y = cvt_pk_bf16(v[2], v[3]); w.z = cvt_pk_bf16(v[4], v[5]); w.w = cvt_pk_bf16(v[6], v[7]);
;                       *(PG8_LAS u32x4*)(stg + fr * 144 + fq * 16 + bj * 64) = w; }
;                 }
;                 {
;                     int kind;
;                     if (odd) kind = (u.pn < 6) ? 0 : (u.pn == 6 ? 1 : 2);
;                     else     kind = (u.pn < 2) ? 0 : (u.pn == 2 ? (wc < 2 ? 1 : 2) : 3);
; #pragma unroll
;                     for (int i = 0; i < 2; ++i) { const int c = fq * 16 + fr + 64 * i, rr = c >> 3, pc = c & 7;
;                         const u32x4 w = *(const PG8_LAS u32x4*)(stg + rr * 144 + pc * 16);
;                         const int rowc = row - fr + rr, posc = rowc & 4095;
;                         if (kind == 1 || kind == 2) {
;                             bf16_t* dst = (kind == 1) ? kd : vt;
;                             if (odd) *(u32x4*)(dst + (size_t)(b * 4 + wc) * (4096 * 64) + (size_t)((posc & 15) * 256 + (posc >> 4)) * 64 + pc * 8) = w;
;                             else     *(u32x4*)(dst + (size_t)(b * 2 + (wc & 1)) * (4096 * 64) + (size_t)posc * 64 + pc * 8) = w;
	s_mov_b32 s100, s98
	s_mov_b32 s101, s99
	global_store_dwordx4 v200, v[122:125], s[100:101] nt
	s_add_u32 s100, s100, s67
	s_addc_u32 s101, s101, 0
	global_store_dwordx4 v200, v[114:117], s[100:101] nt
	v_xor_b32_e32 v226, v201, v226
	v_xor_b32_e32 v227, v201, v227
	v_xor_b32_e32 v228, v201, v228
	v_xor_b32_e32 v229, v201, v229
	v_xor_b32_e32 v230, v201, v230
	v_xor_b32_e32 v231, v201, v231
	v_xor_b32_e32 v232, v201, v232
	v_xor_b32_e32 v233, v201, v233
	s_waitcnt lgkmcnt(4)
	v_mul_f32_e32 v98, v226, v98
	v_fmac_f32_e32 v98, v110, v218
	v_cndmask_b32_e64 v110, v110, v98, s[38:39]
	v_mul_f32_e32 v99, v227, v99
	v_fmac_f32_e32 v99, v111, v219
	v_cndmask_b32_e64 v111, v111, v99, s[38:39]
	v_mul_f32_e32 v100, v228, v100
	v_fmac_f32_e32 v100, v112, v220
	v_cndmask_b32_e64 v112, v112, v100, s[38:39]
	v_mul_f32_e32 v101, v229, v101
	v_fmac_f32_e32 v101, v113, v221
	v_cndmask_b32_e64 v113, v113, v101, s[38:39]
	s_waitcnt lgkmcnt(0)
	v_mul_f32_e32 v162, v230, v162
	v_fmac_f32_e32 v162, v106, v222
	v_cndmask_b32_e64 v106, v106, v162, s[38:39]
	v_mul_f32_e32 v163, v231, v163
	v_fmac_f32_e32 v163, v107, v223
	v_cndmask_b32_e64 v107, v107, v163, s[38:39]
	v_mul_f32_e32 v164, v232, v164
	v_fmac_f32_e32 v164, v108, v224
	v_cndmask_b32_e64 v108, v108, v164, s[38:39]
	v_mul_f32_e32 v165, v233, v165
	v_fmac_f32_e32 v165, v109, v225
	v_cndmask_b32_e64 v109, v109, v165, s[38:39]
	v_pk_mul_f32 v[110:111], v[110:111], s[30:31] op_sel_hi:[1,0]
	v_pk_mul_f32 v[112:113], v[112:113], s[30:31] op_sel_hi:[1,0]
	v_pk_mul_f32 v[106:107], v[106:107], s[30:31] op_sel_hi:[1,0]
	v_pk_mul_f32 v[108:109], v[108:109], s[30:31] op_sel_hi:[1,0]
	v_cvt_pk_bf16_f32 v110, v110, v111
	v_cvt_pk_bf16_f32 v111, v112, v113
	v_cvt_pk_bf16_f32 v112, v106, v107
	v_cvt_pk_bf16_f32 v113, v108, v109
	ds_write_b128 v178, v[110:113]
	ds_write_b128 v178, v[102:105] offset:64
	ds_read_b128 v[106:109], v180
	ds_read_b128 v[98:101], v180 offset:1152
	s_add_i32 s44, s19, 48
	s_and_b32 s44, s44, 0xfff
	s_lshl_b32 s44, s44, 6
	s_add_u32 s44, s62, s44
	s_addc_u32 s45, s63, 0
	global_load_dwordx4 v[158:161], v166, s[44:45]
	s_waitcnt vmcnt(3)
	ds_write_b128 v167, v[154:157]
	ds_read_b128 v[218:221], v168
	ds_read_b128 v[222:225], v168 offset:16
	ds_read_b128 v[226:229], v168 offset:32
	ds_read_b128 v[230:233], v168 offset:48
	v_pk_mul_f32 v[86:87], v[86:87], v[150:151] op_sel_hi:[1,0]
	v_pk_mul_f32 v[88:89], v[88:89], v[150:151] op_sel_hi:[1,0]
	v_pk_mul_f32 v[82:83], v[82:83], v[150:151] op_sel_hi:[1,0]
	v_pk_mul_f32 v[84:85], v[84:85], v[150:151] op_sel_hi:[1,0]
	v_pk_mul_f32 v[86:87], v[86:87], s[30:31] op_sel_hi:[1,0]
	v_pk_mul_f32 v[88:89], v[88:89], s[30:31] op_sel_hi:[1,0]
	v_pk_mul_f32 v[82:83], v[82:83], s[30:31] op_sel_hi:[1,0]
	v_pk_mul_f32 v[84:85], v[84:85], s[30:31] op_sel_hi:[1,0]
	v_cvt_pk_bf16_f32 v86, v86, v87
	v_cvt_pk_bf16_f32 v87, v88, v89
	v_cvt_pk_bf16_f32 v88, v82, v83
	v_cvt_pk_bf16_f32 v89, v84, v85
	v_pk_mul_f32 v[94:95], v[94:95], v[150:151] op_sel_hi:[1,0]
	v_pk_mul_f32 v[96:97], v[96:97], v[150:151] op_sel_hi:[1,0]
	v_pk_mul_f32 v[90:91], v[90:91], v[150:151] op_sel_hi:[1,0]
	v_pk_mul_f32 v[92:93], v[92:93], v[150:151] op_sel_hi:[1,0]
	ds_swizzle_b32 v82, v94 offset:0x401f
	ds_swizzle_b32 v83, v95 offset:0x401f
	ds_swizzle_b32 v84, v96 offset:0x401f
	ds_swizzle_b32 v85, v97 offset:0x401f
	ds_swizzle_b32 v162, v90 offset:0x401f
	ds_swizzle_b32 v163, v91 offset:0x401f
	ds_swizzle_b32 v164, v92 offset:0x401f
	ds_swizzle_b32 v165, v93 offset:0x401f
	s_waitcnt lgkmcnt(8)
	s_mul_i32 s44, s66, 16
	s_add_u32 s100, s98, s44
	s_addc_u32 s101, s99, 0
	global_store_dwordx4 v200, v[106:109], s[100:101] nt
	s_add_u32 s100, s100, s67
	s_addc_u32 s101, s101, 0
	global_store_dwordx4 v200, v[98:101], s[100:101] nt
	v_xor_b32_e32 v226, v201, v226
	v_xor_b32_e32 v227, v201, v227
	v_xor_b32_e32 v228, v201, v228
	v_xor_b32_e32 v229, v201, v229
	v_xor_b32_e32 v230, v201, v230
	v_xor_b32_e32 v231, v201, v231
	v_xor_b32_e32 v232, v201, v232
	v_xor_b32_e32 v233, v201, v233
	s_waitcnt lgkmcnt(4)
	v_mul_f32_e32 v82, v226, v82
	v_fmac_f32_e32 v82, v94, v218
	v_cndmask_b32_e64 v94, v94, v82, s[38:39]
	v_mul_f32_e32 v83, v227, v83
	v_fmac_f32_e32 v83, v95, v219
	v_cndmask_b32_e64 v95, v95, v83, s[38:39]
	v_mul_f32_e32 v84, v228, v84
	v_fmac_f32_e32 v84, v96, v220
	v_cndmask_b32_e64 v96, v96, v84, s[38:39]
	v_mul_f32_e32 v85, v229, v85
	v_fmac_f32_e32 v85, v97, v221
	v_cndmask_b32_e64 v97, v97, v85, s[38:39]
	s_waitcnt lgkmcnt(0)
	v_mul_f32_e32 v162, v230, v162
	v_fmac_f32_e32 v162, v90, v222
	v_cndmask_b32_e64 v90, v90, v162, s[38:39]
	v_mul_f32_e32 v163, v231, v163
	v_fmac_f32_e32 v163, v91, v223
	v_cndmask_b32_e64 v91, v91, v163, s[38:39]
	v_mul_f32_e32 v164, v232, v164
	v_fmac_f32_e32 v164, v92, v224
	v_cndmask_b32_e64 v92, v92, v164, s[38:39]
	v_mul_f32_e32 v165, v233, v165
	v_fmac_f32_e32 v165, v93, v225
	v_cndmask_b32_e64 v93, v93, v165, s[38:39]
	v_pk_mul_f32 v[94:95], v[94:95], s[30:31] op_sel_hi:[1,0]
	v_pk_mul_f32 v[96:97], v[96:97], s[30:31] op_sel_hi:[1,0]
	v_pk_mul_f32 v[90:91], v[90:91], s[30:31] op_sel_hi:[1,0]
	v_pk_mul_f32 v[92:93], v[92:93], s[30:31] op_sel_hi:[1,0]
	v_cvt_pk_bf16_f32 v94, v94, v95
	v_cvt_pk_bf16_f32 v95, v96, v97
	v_cvt_pk_bf16_f32 v96, v90, v91
	v_cvt_pk_bf16_f32 v97, v92, v93
	ds_write_b128 v178, v[94:97]
	ds_write_b128 v178, v[86:89] offset:64
	ds_read_b128 v[90:93], v180
	ds_read_b128 v[82:85], v180 offset:1152
	s_add_i32 s44, s19, 128
	s_and_b32 s44, s44, 0xfff
	s_lshl_b32 s44, s44, 6
	s_add_u32 s44, s62, s44
	s_addc_u32 s45, s63, 0
	global_load_dwordx4 v[154:157], v166, s[44:45]
	s_waitcnt vmcnt(3)
;     __device__ __forceinline__ void operator()(const f32x4 (&acc)[2][2][4][2], const Unit& u, int wr, int wc, int fr, int fq, PG8_LAS float* stash, int par, PG8_LAS unsigned char* stg, const Unit& un) const {
;     ...
;                     for (int i = 0; i < 4; ++i) { v[i] = acc[ai][bj][m][0][i] * rs; v[4 + i] = acc[ai][bj][m][1][i] * rs; }
;                     if (kind <= 1 && bj == 0) {
;                         const f32x4 c0 = *(const f32x4*)(cs + pos * 16), c1 = *(const f32x4*)(cs + pos * 16 + 4), s0 = *(const f32x4*)(cs + pos * 16 + 8), s1 = *(const f32x4*)(cs + pos * 16 + 12);
; #pragma unroll
;                         for (int i = 0; i < 8; ++i) {
;                             const float c = i < 4 ? c0[i & 3] : c1[i & 3], s = i < 4 ? s0[i & 3] : s1[i & 3];
;                             const float pr = peer_x16(v[i], fq);
;                             const float r = (fq == 0) ? (v[i] * c - pr * s) : (v[i] * c + pr * s);
;                             v[i] = (fq < 2) ? r : v[i];
;                         }
;                     }
;                     if (kind == 0) {
; #pragma unroll
;                         for (int i = 0; i < 8; ++i) v[i] *= C2Q;
;                     }
;                     { u32x4 w; w.x = cvt_pk_bf16(v[0], v[1]); w.y = cvt_pk_bf16(v[2], v[3]); w.z = cvt_pk_bf16(v[4], v[5]); w.w = cvt_pk_bf16(v[6], v[7]);
;                       *(PG8_LAS u32x4*)(stg + fr * 144 + fq * 16 + bj * 64) = w; }
;                 }
;                 {
;                     int kind;
;                     if (odd) kind = (u.pn < 6) ? 0 : (u.pn == 6 ? 1 : 2);
;                     else     kind = (u.pn < 2) ? 0 : (u.pn == 2 ? (wc < 2 ? 1 : 2) : 3);
; #pragma unroll
;                     for (int i = 0; i < 2; ++i) { const int c = fq * 16 + fr + 64 * i, rr = c >> 3, pc = c & 7;
;                         const u32x4 w = *(const PG8_LAS u32x4*)(stg + rr * 144 + pc * 16);
;                         const int rowc = row - fr + rr, posc = rowc & 4095;
;                         if (kind == 1 || kind == 2) {
;                             bf16_t* dst = (kind == 1) ? kd : vt;
;                             if (odd) *(u32x4*)(dst + (size_t)(b * 4 + wc) * (4096 * 64) + (size_t)((posc & 15) * 256 + (posc >> 4)) * 64 + pc * 8) = w;
;                             else     *(u32x4*)(dst + (size_t)(b * 2 + (wc & 1)) * (4096 * 64) + (size_t)posc * 64 + pc * 8) = w;
	ds_write_b128 v167, v[158:161]
	ds_read_b128 v[218:221], v168
	ds_read_b128 v[222:225], v168 offset:16
	ds_read_b128 v[226:229], v168 offset:32
	ds_read_b128 v[230:233], v168 offset:48
	v_pk_mul_f32 v[70:71], v[70:71], v[150:151] op_sel:[0,1]
	v_pk_mul_f32 v[72:73], v[72:73], v[150:151] op_sel:[0,1]
	v_pk_mul_f32 v[66:67], v[66:67], v[150:151] op_sel:[0,1]
	v_pk_mul_f32 v[68:69], v[68:69], v[150:151] op_sel:[0,1]
	v_pk_mul_f32 v[70:71], v[70:71], s[30:31] op_sel_hi:[1,0]
	v_pk_mul_f32 v[72:73], v[72:73], s[30:31] op_sel_hi:[1,0]
	v_pk_mul_f32 v[66:67], v[66:67], s[30:31] op_sel_hi:[1,0]
	v_pk_mul_f32 v[68:69], v[68:69], s[30:31] op_sel_hi:[1,0]
	v_cvt_pk_bf16_f32 v70, v70, v71
	v_cvt_pk_bf16_f32 v71, v72, v73
	v_cvt_pk_bf16_f32 v72, v66, v67
	v_cvt_pk_bf16_f32 v73, v68, v69
	v_pk_mul_f32 v[78:79], v[78:79], v[150:151] op_sel:[0,1]
	v_pk_mul_f32 v[80:81], v[80:81], v[150:151] op_sel:[0,1]
	v_pk_mul_f32 v[74:75], v[74:75], v[150:151] op_sel:[0,1]
	v_pk_mul_f32 v[76:77], v[76:77], v[150:151] op_sel:[0,1]
	ds_swizzle_b32 v66, v78 offset:0x401f
	ds_swizzle_b32 v67, v79 offset:0x401f
	ds_swizzle_b32 v68, v80 offset:0x401f
	ds_swizzle_b32 v69, v81 offset:0x401f
	ds_swizzle_b32 v162, v74 offset:0x401f
	ds_swizzle_b32 v163, v75 offset:0x401f
	ds_swizzle_b32 v164, v76 offset:0x401f
	ds_swizzle_b32 v165, v77 offset:0x401f
	s_waitcnt lgkmcnt(8)
	s_mul_i32 s44, s66, 32
	s_add_u32 s100, s98, s44
	s_addc_u32 s101, s99, 0
	global_store_dwordx4 v200, v[90:93], s[100:101] nt
	s_add_u32 s100, s100, s67
	s_addc_u32 s101, s101, 0
	global_store_dwordx4 v200, v[82:85], s[100:101] nt
	v_xor_b32_e32 v226, v201, v226
	v_xor_b32_e32 v227, v201, v227
	v_xor_b32_e32 v228, v201, v228
	v_xor_b32_e32 v229, v201, v229
	v_xor_b32_e32 v230, v201, v230
	v_xor_b32_e32 v231, v201, v231
	v_xor_b32_e32 v232, v201, v232
	v_xor_b32_e32 v233, v201, v233
	s_waitcnt lgkmcnt(4)
	v_mul_f32_e32 v66, v226, v66
	v_fmac_f32_e32 v66, v78, v218
	v_cndmask_b32_e64 v78, v78, v66, s[38:39]
	v_mul_f32_e32 v67, v227, v67
	v_fmac_f32_e32 v67, v79, v219
	v_cndmask_b32_e64 v79, v79, v67, s[38:39]
	v_mul_f32_e32 v68, v228, v68
	v_fmac_f32_e32 v68, v80, v220
	v_cndmask_b32_e64 v80, v80, v68, s[38:39]
	v_mul_f32_e32 v69, v229, v69
	v_fmac_f32_e32 v69, v81, v221
	v_cndmask_b32_e64 v81, v81, v69, s[38:39]
	s_waitcnt lgkmcnt(0)
	v_mul_f32_e32 v162, v230, v162
	v_fmac_f32_e32 v162, v74, v222
	v_cndmask_b32_e64 v74, v74, v162, s[38:39]
	v_mul_f32_e32 v163, v231, v163
	v_fmac_f32_e32 v163, v75, v223
	v_cndmask_b32_e64 v75, v75, v163, s[38:39]
	v_mul_f32_e32 v164, v232, v164
	v_fmac_f32_e32 v164, v76, v224
	v_cndmask_b32_e64 v76, v76, v164, s[38:39]
	v_mul_f32_e32 v165, v233, v165
	v_fmac_f32_e32 v165, v77, v225
	v_cndmask_b32_e64 v77, v77, v165, s[38:39]
	v_pk_mul_f32 v[78:79], v[78:79], s[30:31] op_sel_hi:[1,0]
	v_pk_mul_f32 v[80:81], v[80:81], s[30:31] op_sel_hi:[1,0]
	v_pk_mul_f32 v[74:75], v[74:75], s[30:31] op_sel_hi:[1,0]
	v_pk_mul_f32 v[76:77], v[76:77], s[30:31] op_sel_hi:[1,0]
	v_cvt_pk_bf16_f32 v78, v78, v79
	v_cvt_pk_bf16_f32 v79, v80, v81
	v_cvt_pk_bf16_f32 v80, v74, v75
	v_cvt_pk_bf16_f32 v81, v76, v77
	ds_write_b128 v178, v[78:81]
	ds_write_b128 v178, v[70:73] offset:64
	ds_read_b128 v[74:77], v180
	ds_read_b128 v[66:69], v180 offset:1152
	s_add_i32 s44, s19, 144
	s_and_b32 s44, s44, 0xfff
	s_lshl_b32 s44, s44, 6
	s_add_u32 s44, s62, s44
	s_addc_u32 s45, s63, 0
	global_load_dwordx4 v[158:161], v166, s[44:45]
	s_waitcnt vmcnt(3)
	ds_write_b128 v167, v[154:157]
	ds_read_b128 v[218:221], v168
	ds_read_b128 v[222:225], v168 offset:16
	ds_read_b128 v[226:229], v168 offset:32
	ds_read_b128 v[230:233], v168 offset:48
	v_pk_mul_f32 v[54:55], v[54:55], v[148:149] op_sel_hi:[1,0]
	v_pk_mul_f32 v[56:57], v[56:57], v[148:149] op_sel_hi:[1,0]
	v_pk_mul_f32 v[50:51], v[50:51], v[148:149] op_sel_hi:[1,0]
	v_pk_mul_f32 v[52:53], v[52:53], v[148:149] op_sel_hi:[1,0]
	v_pk_mul_f32 v[54:55], v[54:55], s[30:31] op_sel_hi:[1,0]
	v_pk_mul_f32 v[56:57], v[56:57], s[30:31] op_sel_hi:[1,0]
	v_pk_mul_f32 v[50:51], v[50:51], s[30:31] op_sel_hi:[1,0]
	v_pk_mul_f32 v[52:53], v[52:53], s[30:31] op_sel_hi:[1,0]
	v_cvt_pk_bf16_f32 v54, v54, v55
	v_cvt_pk_bf16_f32 v55, v56, v57
	v_cvt_pk_bf16_f32 v56, v50, v51
	v_cvt_pk_bf16_f32 v57, v52, v53
	v_pk_mul_f32 v[62:63], v[62:63], v[148:149] op_sel_hi:[1,0]
	v_pk_mul_f32 v[64:65], v[64:65], v[148:149] op_sel_hi:[1,0]
	v_pk_mul_f32 v[58:59], v[58:59], v[148:149] op_sel_hi:[1,0]
	v_pk_mul_f32 v[60:61], v[60:61], v[148:149] op_sel_hi:[1,0]
	ds_swizzle_b32 v50, v62 offset:0x401f
	ds_swizzle_b32 v51, v63 offset:0x401f
	ds_swizzle_b32 v52, v64 offset:0x401f
	ds_swizzle_b32 v53, v65 offset:0x401f
	ds_swizzle_b32 v162, v58 offset:0x401f
	ds_swizzle_b32 v163, v59 offset:0x401f
	ds_swizzle_b32 v164, v60 offset:0x401f
	ds_swizzle_b32 v165, v61 offset:0x401f
	s_waitcnt lgkmcnt(8)
	s_mul_i32 s44, s66, 48
	s_add_u32 s100, s98, s44
	s_addc_u32 s101, s99, 0
	global_store_dwordx4 v200, v[74:77], s[100:101] nt
	s_add_u32 s100, s100, s67
	s_addc_u32 s101, s101, 0
	global_store_dwordx4 v200, v[66:69], s[100:101] nt
	v_xor_b32_e32 v226, v201, v226
	v_xor_b32_e32 v227, v201, v227
	v_xor_b32_e32 v228, v201, v228
	v_xor_b32_e32 v229, v201, v229
	v_xor_b32_e32 v230, v201, v230
	v_xor_b32_e32 v231, v201, v231
	v_xor_b32_e32 v232, v201, v232
	v_xor_b32_e32 v233, v201, v233
	s_waitcnt lgkmcnt(4)
	v_mul_f32_e32 v50, v226, v50
	v_fmac_f32_e32 v50, v62, v218
	v_cndmask_b32_e64 v62, v62, v50, s[38:39]
	v_mul_f32_e32 v51, v227, v51
	v_fmac_f32_e32 v51, v63, v219
	v_cndmask_b32_e64 v63, v63, v51, s[38:39]
	v_mul_f32_e32 v52, v228, v52
	v_fmac_f32_e32 v52, v64, v220
	v_cndmask_b32_e64 v64, v64, v52, s[38:39]
	v_mul_f32_e32 v53, v229, v53
	v_fmac_f32_e32 v53, v65, v221
	v_cndmask_b32_e64 v65, v65, v53, s[38:39]
	s_waitcnt lgkmcnt(0)
;     __device__ __forceinline__ void operator()(const f32x4 (&acc)[2][2][4][2], const Unit& u, int wr, int wc, int fr, int fq, PG8_LAS float* stash, int par, PG8_LAS unsigned char* stg, const Unit& un) const {
;     ...
;                     for (int i = 0; i < 4; ++i) { v[i] = acc[ai][bj][m][0][i] * rs; v[4 + i] = acc[ai][bj][m][1][i] * rs; }
;                     if (kind <= 1 && bj == 0) {
;                         const f32x4 c0 = *(const f32x4*)(cs + pos * 16), c1 = *(const f32x4*)(cs + pos * 16 + 4), s0 = *(const f32x4*)(cs + pos * 16 + 8), s1 = *(const f32x4*)(cs + pos * 16 + 12);
; #pragma unroll
;                         for (int i = 0; i < 8; ++i) {
;                             const float c = i < 4 ? c0[i & 3] : c1[i & 3], s = i < 4 ? s0[i & 3] : s1[i & 3];
;                             const float pr = peer_x16(v[i], fq);
;                             const float r = (fq == 0) ? (v[i] * c - pr * s) : (v[i] * c + pr * s);
;                             v[i] = (fq < 2) ? r : v[i];
;                         }
;                     }
;                     if (kind == 0) {
; #pragma unroll
;                         for (int i = 0; i < 8; ++i) v[i] *= C2Q;
;                     }
;                     { u32x4 w; w.x = cvt_pk_bf16(v[0], v[1]); w.y = cvt_pk_bf16(v[2], v[3]); w.z = cvt_pk_bf16(v[4], v[5]); w.w = cvt_pk_bf16(v[6], v[7]);
;                       *(PG8_LAS u32x4*)(stg + fr * 144 + fq * 16 + bj * 64) = w; }
;                 }
;                 {
;                     int kind;
;                     if (odd) kind = (u.pn < 6) ? 0 : (u.pn == 6 ? 1 : 2);
;                     else     kind = (u.pn < 2) ? 0 : (u.pn == 2 ? (wc < 2 ? 1 : 2) : 3);
; #pragma unroll
;                     for (int i = 0; i < 2; ++i) { const int c = fq * 16 + fr + 64 * i, rr = c >> 3, pc = c & 7;
;                         const u32x4 w = *(const PG8_LAS u32x4*)(stg + rr * 144 + pc * 16);
;                         const int rowc = row - fr + rr, posc = rowc & 4095;
;                         if (kind == 1 || kind == 2) {
;                             bf16_t* dst = (kind == 1) ? kd : vt;
;                             if (odd) *(u32x4*)(dst + (size_t)(b * 4 + wc) * (4096 * 64) + (size_t)((posc & 15) * 256 + (posc >> 4)) * 64 + pc * 8) = w;
;                             else     *(u32x4*)(dst + (size_t)(b * 2 + (wc & 1)) * (4096 * 64) + (size_t)posc * 64 + pc * 8) = w;
	v_mul_f32_e32 v162, v230, v162
	v_fmac_f32_e32 v162, v58, v222
	v_cndmask_b32_e64 v58, v58, v162, s[38:39]
	v_mul_f32_e32 v163, v231, v163
	v_fmac_f32_e32 v163, v59, v223
	v_cndmask_b32_e64 v59, v59, v163, s[38:39]
	v_mul_f32_e32 v164, v232, v164
	v_fmac_f32_e32 v164, v60, v224
	v_cndmask_b32_e64 v60, v60, v164, s[38:39]
	v_mul_f32_e32 v165, v233, v165
	v_fmac_f32_e32 v165, v61, v225
	v_cndmask_b32_e64 v61, v61, v165, s[38:39]
	v_pk_mul_f32 v[62:63], v[62:63], s[30:31] op_sel_hi:[1,0]
	v_pk_mul_f32 v[64:65], v[64:65], s[30:31] op_sel_hi:[1,0]
	v_pk_mul_f32 v[58:59], v[58:59], s[30:31] op_sel_hi:[1,0]
	v_pk_mul_f32 v[60:61], v[60:61], s[30:31] op_sel_hi:[1,0]
	v_cvt_pk_bf16_f32 v62, v62, v63
	v_cvt_pk_bf16_f32 v63, v64, v65
	v_cvt_pk_bf16_f32 v64, v58, v59
	v_cvt_pk_bf16_f32 v65, v60, v61
	ds_write_b128 v178, v[62:65]
	ds_write_b128 v178, v[54:57] offset:64
	ds_read_b128 v[58:61], v180
	ds_read_b128 v[50:53], v180 offset:1152
	s_add_i32 s44, s19, 160
	s_and_b32 s44, s44, 0xfff
	s_lshl_b32 s44, s44, 6
	s_add_u32 s44, s62, s44
	s_addc_u32 s45, s63, 0
	global_load_dwordx4 v[154:157], v166, s[44:45]
	s_waitcnt vmcnt(3)
	ds_write_b128 v167, v[158:161]
	ds_read_b128 v[218:221], v168
	ds_read_b128 v[222:225], v168 offset:16
	ds_read_b128 v[226:229], v168 offset:32
	ds_read_b128 v[230:233], v168 offset:48
	v_pk_mul_f32 v[38:39], v[38:39], v[148:149] op_sel:[0,1]
	v_pk_mul_f32 v[40:41], v[40:41], v[148:149] op_sel:[0,1]
	v_pk_mul_f32 v[34:35], v[34:35], v[148:149] op_sel:[0,1]
	v_pk_mul_f32 v[36:37], v[36:37], v[148:149] op_sel:[0,1]
	v_pk_mul_f32 v[38:39], v[38:39], s[30:31] op_sel_hi:[1,0]
	v_pk_mul_f32 v[40:41], v[40:41], s[30:31] op_sel_hi:[1,0]
	v_pk_mul_f32 v[34:35], v[34:35], s[30:31] op_sel_hi:[1,0]
	v_pk_mul_f32 v[36:37], v[36:37], s[30:31] op_sel_hi:[1,0]
	v_cvt_pk_bf16_f32 v38, v38, v39
	v_cvt_pk_bf16_f32 v39, v40, v41
	v_cvt_pk_bf16_f32 v40, v34, v35
	v_cvt_pk_bf16_f32 v41, v36, v37
	v_pk_mul_f32 v[46:47], v[46:47], v[148:149] op_sel:[0,1]
	v_pk_mul_f32 v[48:49], v[48:49], v[148:149] op_sel:[0,1]
	v_pk_mul_f32 v[42:43], v[42:43], v[148:149] op_sel:[0,1]
	v_pk_mul_f32 v[44:45], v[44:45], v[148:149] op_sel:[0,1]
	ds_swizzle_b32 v34, v46 offset:0x401f
	ds_swizzle_b32 v35, v47 offset:0x401f
	ds_swizzle_b32 v36, v48 offset:0x401f
	ds_swizzle_b32 v37, v49 offset:0x401f
	ds_swizzle_b32 v162, v42 offset:0x401f
	ds_swizzle_b32 v163, v43 offset:0x401f
	ds_swizzle_b32 v164, v44 offset:0x401f
	ds_swizzle_b32 v165, v45 offset:0x401f
	s_waitcnt lgkmcnt(8)
	s_mul_i32 s44, s66, 128
	s_add_u32 s100, s98, s44
	s_addc_u32 s101, s99, 0
	global_store_dwordx4 v200, v[58:61], s[100:101] nt
	s_add_u32 s100, s100, s67
	s_addc_u32 s101, s101, 0
	global_store_dwordx4 v200, v[50:53], s[100:101] nt
	v_xor_b32_e32 v226, v201, v226
	v_xor_b32_e32 v227, v201, v227
	v_xor_b32_e32 v228, v201, v228
	v_xor_b32_e32 v229, v201, v229
	v_xor_b32_e32 v230, v201, v230
	v_xor_b32_e32 v231, v201, v231
	v_xor_b32_e32 v232, v201, v232
	v_xor_b32_e32 v233, v201, v233
	s_waitcnt lgkmcnt(4)
	v_mul_f32_e32 v34, v226, v34
	v_fmac_f32_e32 v34, v46, v218
	v_cndmask_b32_e64 v46, v46, v34, s[38:39]
	v_mul_f32_e32 v35, v227, v35
	v_fmac_f32_e32 v35, v47, v219
	v_cndmask_b32_e64 v47, v47, v35, s[38:39]
	v_mul_f32_e32 v36, v228, v36
	v_fmac_f32_e32 v36, v48, v220
	v_cndmask_b32_e64 v48, v48, v36, s[38:39]
	v_mul_f32_e32 v37, v229, v37
	v_fmac_f32_e32 v37, v49, v221
	v_cndmask_b32_e64 v49, v49, v37, s[38:39]
	s_waitcnt lgkmcnt(0)
	v_mul_f32_e32 v162, v230, v162
	v_fmac_f32_e32 v162, v42, v222
	v_cndmask_b32_e64 v42, v42, v162, s[38:39]
	v_mul_f32_e32 v163, v231, v163
	v_fmac_f32_e32 v163, v43, v223
	v_cndmask_b32_e64 v43, v43, v163, s[38:39]
	v_mul_f32_e32 v164, v232, v164
	v_fmac_f32_e32 v164, v44, v224
	v_cndmask_b32_e64 v44, v44, v164, s[38:39]
	v_mul_f32_e32 v165, v233, v165
	v_fmac_f32_e32 v165, v45, v225
	v_cndmask_b32_e64 v45, v45, v165, s[38:39]
	v_pk_mul_f32 v[46:47], v[46:47], s[30:31] op_sel_hi:[1,0]
	v_pk_mul_f32 v[48:49], v[48:49], s[30:31] op_sel_hi:[1,0]
	v_pk_mul_f32 v[42:43], v[42:43], s[30:31] op_sel_hi:[1,0]
	v_pk_mul_f32 v[44:45], v[44:45], s[30:31] op_sel_hi:[1,0]
	v_cvt_pk_bf16_f32 v46, v46, v47
	v_cvt_pk_bf16_f32 v47, v48, v49
	v_cvt_pk_bf16_f32 v48, v42, v43
	v_cvt_pk_bf16_f32 v49, v44, v45
	ds_write_b128 v178, v[46:49]
	ds_write_b128 v178, v[38:41] offset:64
	ds_read_b128 v[42:45], v180
	ds_read_b128 v[34:37], v180 offset:1152
	s_add_i32 s44, s19, 176
	s_and_b32 s44, s44, 0xfff
	s_lshl_b32 s44, s44, 6
	s_add_u32 s44, s62, s44
	s_addc_u32 s45, s63, 0
	global_load_dwordx4 v[158:161], v166, s[44:45]
	s_waitcnt vmcnt(3)
	ds_write_b128 v167, v[154:157]
	ds_read_b128 v[218:221], v168
	ds_read_b128 v[222:225], v168 offset:16
	ds_read_b128 v[226:229], v168 offset:32
	ds_read_b128 v[230:233], v168 offset:48
	v_pk_mul_f32 v[22:23], v[22:23], v[146:147] op_sel_hi:[1,0]
	v_pk_mul_f32 v[24:25], v[24:25], v[146:147] op_sel_hi:[1,0]
	v_pk_mul_f32 v[18:19], v[18:19], v[146:147] op_sel_hi:[1,0]
	v_pk_mul_f32 v[20:21], v[20:21], v[146:147] op_sel_hi:[1,0]
	v_pk_mul_f32 v[22:23], v[22:23], s[30:31] op_sel_hi:[1,0]
	v_pk_mul_f32 v[24:25], v[24:25], s[30:31] op_sel_hi:[1,0]
	v_pk_mul_f32 v[18:19], v[18:19], s[30:31] op_sel_hi:[1,0]
	v_pk_mul_f32 v[20:21], v[20:21], s[30:31] op_sel_hi:[1,0]
	v_cvt_pk_bf16_f32 v22, v22, v23
	v_cvt_pk_bf16_f32 v23, v24, v25
	v_cvt_pk_bf16_f32 v24, v18, v19
	v_cvt_pk_bf16_f32 v25, v20, v21
	v_pk_mul_f32 v[30:31], v[30:31], v[146:147] op_sel_hi:[1,0]
	v_pk_mul_f32 v[32:33], v[32:33], v[146:147] op_sel_hi:[1,0]
	v_pk_mul_f32 v[26:27], v[26:27], v[146:147] op_sel_hi:[1,0]
	v_pk_mul_f32 v[28:29], v[28:29], v[146:147] op_sel_hi:[1,0]
	ds_swizzle_b32 v18, v30 offset:0x401f
	ds_swizzle_b32 v19, v31 offset:0x401f
	ds_swizzle_b32 v20, v32 offset:0x401f
	ds_swizzle_b32 v21, v33 offset:0x401f
	ds_swizzle_b32 v162, v26 offset:0x401f
	ds_swizzle_b32 v163, v27 offset:0x401f
	ds_swizzle_b32 v164, v28 offset:0x401f
	ds_swizzle_b32 v165, v29 offset:0x401f
	s_waitcnt lgkmcnt(8)
;     __device__ __forceinline__ void operator()(const f32x4 (&acc)[2][2][4][2], const Unit& u, int wr, int wc, int fr, int fq, PG8_LAS float* stash, int par, PG8_LAS unsigned char* stg, const Unit& un) const {
;     ...
;                     for (int i = 0; i < 4; ++i) { v[i] = acc[ai][bj][m][0][i] * rs; v[4 + i] = acc[ai][bj][m][1][i] * rs; }
;                     if (kind <= 1 && bj == 0) {
;                         const f32x4 c0 = *(const f32x4*)(cs + pos * 16), c1 = *(const f32x4*)(cs + pos * 16 + 4), s0 = *(const f32x4*)(cs + pos * 16 + 8), s1 = *(const f32x4*)(cs + pos * 16 + 12);
; #pragma unroll
;                         for (int i = 0; i < 8; ++i) {
;                             const float c = i < 4 ? c0[i & 3] : c1[i & 3], s = i < 4 ? s0[i & 3] : s1[i & 3];
;                             const float pr = peer_x16(v[i], fq);
;                             const float r = (fq == 0) ? (v[i] * c - pr * s) : (v[i] * c + pr * s);
;                             v[i] = (fq < 2) ? r : v[i];
;                         }
;                     }
;                     if (kind == 0) {
; #pragma unroll
;                         for (int i = 0; i < 8; ++i) v[i] *= C2Q;
;                     }
;                     { u32x4 w; w.x = cvt_pk_bf16(v[0], v[1]); w.y = cvt_pk_bf16(v[2], v[3]); w.z = cvt_pk_bf16(v[4], v[5]); w.w = cvt_pk_bf16(v[6], v[7]);
;                       *(PG8_LAS u32x4*)(stg + fr * 144 + fq * 16 + bj * 64) = w; }
;                 }
;                 {
;                     int kind;
;                     if (odd) kind = (u.pn < 6) ? 0 : (u.pn == 6 ? 1 : 2);
;                     else     kind = (u.pn < 2) ? 0 : (u.pn == 2 ? (wc < 2 ? 1 : 2) : 3);
; #pragma unroll
;                     for (int i = 0; i < 2; ++i) { const int c = fq * 16 + fr + 64 * i, rr = c >> 3, pc = c & 7;
;                         const u32x4 w = *(const PG8_LAS u32x4*)(stg + rr * 144 + pc * 16);
;                         const int rowc = row - fr + rr, posc = rowc & 4095;
;                         if (kind == 1 || kind == 2) {
;                             bf16_t* dst = (kind == 1) ? kd : vt;
;                             if (odd) *(u32x4*)(dst + (size_t)(b * 4 + wc) * (4096 * 64) + (size_t)((posc & 15) * 256 + (posc >> 4)) * 64 + pc * 8) = w;
;                             else     *(u32x4*)(dst + (size_t)(b * 2 + (wc & 1)) * (4096 * 64) + (size_t)posc * 64 + pc * 8) = w;
	s_mul_i32 s44, s66, 144
	s_add_u32 s100, s98, s44
	s_addc_u32 s101, s99, 0
	global_store_dwordx4 v200, v[42:45], s[100:101] nt
	s_add_u32 s100, s100, s67
	s_addc_u32 s101, s101, 0
	global_store_dwordx4 v200, v[34:37], s[100:101] nt
	v_xor_b32_e32 v226, v201, v226
	v_xor_b32_e32 v227, v201, v227
	v_xor_b32_e32 v228, v201, v228
	v_xor_b32_e32 v229, v201, v229
	v_xor_b32_e32 v230, v201, v230
	v_xor_b32_e32 v231, v201, v231
	v_xor_b32_e32 v232, v201, v232
	v_xor_b32_e32 v233, v201, v233
	s_waitcnt lgkmcnt(4)
	v_mul_f32_e32 v18, v226, v18
	v_fmac_f32_e32 v18, v30, v218
	v_cndmask_b32_e64 v30, v30, v18, s[38:39]
	v_mul_f32_e32 v19, v227, v19
	v_fmac_f32_e32 v19, v31, v219
	v_cndmask_b32_e64 v31, v31, v19, s[38:39]
	v_mul_f32_e32 v20, v228, v20
	v_fmac_f32_e32 v20, v32, v220
	v_cndmask_b32_e64 v32, v32, v20, s[38:39]
	v_mul_f32_e32 v21, v229, v21
	v_fmac_f32_e32 v21, v33, v221
	v_cndmask_b32_e64 v33, v33, v21, s[38:39]
	s_waitcnt lgkmcnt(0)
	v_mul_f32_e32 v162, v230, v162
	v_fmac_f32_e32 v162, v26, v222
	v_cndmask_b32_e64 v26, v26, v162, s[38:39]
	v_mul_f32_e32 v163, v231, v163
	v_fmac_f32_e32 v163, v27, v223
	v_cndmask_b32_e64 v27, v27, v163, s[38:39]
	v_mul_f32_e32 v164, v232, v164
	v_fmac_f32_e32 v164, v28, v224
	v_cndmask_b32_e64 v28, v28, v164, s[38:39]
	v_mul_f32_e32 v165, v233, v165
	v_fmac_f32_e32 v165, v29, v225
	v_cndmask_b32_e64 v29, v29, v165, s[38:39]
	v_pk_mul_f32 v[30:31], v[30:31], s[30:31] op_sel_hi:[1,0]
	v_pk_mul_f32 v[32:33], v[32:33], s[30:31] op_sel_hi:[1,0]
	v_pk_mul_f32 v[26:27], v[26:27], s[30:31] op_sel_hi:[1,0]
	v_pk_mul_f32 v[28:29], v[28:29], s[30:31] op_sel_hi:[1,0]
	v_cvt_pk_bf16_f32 v30, v30, v31
	v_cvt_pk_bf16_f32 v31, v32, v33
	v_cvt_pk_bf16_f32 v32, v26, v27
	v_cvt_pk_bf16_f32 v33, v28, v29
	ds_write_b128 v178, v[30:33]
	ds_write_b128 v178, v[22:25] offset:64
	ds_read_b128 v[26:29], v180
	ds_read_b128 v[18:21], v180 offset:1152
	s_waitcnt vmcnt(2)
	ds_write_b128 v167, v[158:161]
	ds_read_b128 v[218:221], v168
	ds_read_b128 v[222:225], v168 offset:16
	ds_read_b128 v[226:229], v168 offset:32
	ds_read_b128 v[230:233], v168 offset:48
	v_pk_mul_f32 v[6:7], v[6:7], v[146:147] op_sel:[0,1]
	v_pk_mul_f32 v[8:9], v[8:9], v[146:147] op_sel:[0,1]
	v_pk_mul_f32 v[2:3], v[2:3], v[146:147] op_sel:[0,1]
	v_pk_mul_f32 v[4:5], v[4:5], v[146:147] op_sel:[0,1]
	v_pk_mul_f32 v[6:7], v[6:7], s[30:31] op_sel_hi:[1,0]
	v_pk_mul_f32 v[8:9], v[8:9], s[30:31] op_sel_hi:[1,0]
	v_pk_mul_f32 v[2:3], v[2:3], s[30:31] op_sel_hi:[1,0]
	v_pk_mul_f32 v[4:5], v[4:5], s[30:31] op_sel_hi:[1,0]
	v_cvt_pk_bf16_f32 v6, v6, v7
	v_cvt_pk_bf16_f32 v7, v8, v9
	v_cvt_pk_bf16_f32 v8, v2, v3
	v_cvt_pk_bf16_f32 v9, v4, v5
	v_pk_mul_f32 v[14:15], v[14:15], v[146:147] op_sel:[0,1]
	v_pk_mul_f32 v[16:17], v[16:17], v[146:147] op_sel:[0,1]
	v_pk_mul_f32 v[10:11], v[10:11], v[146:147] op_sel:[0,1]
	v_pk_mul_f32 v[12:13], v[12:13], v[146:147] op_sel:[0,1]
	ds_swizzle_b32 v2, v14 offset:0x401f
	ds_swizzle_b32 v3, v15 offset:0x401f
	ds_swizzle_b32 v4, v16 offset:0x401f
	ds_swizzle_b32 v5, v17 offset:0x401f
	ds_swizzle_b32 v162, v10 offset:0x401f
	ds_swizzle_b32 v163, v11 offset:0x401f
	ds_swizzle_b32 v164, v12 offset:0x401f
	ds_swizzle_b32 v165, v13 offset:0x401f
	s_waitcnt lgkmcnt(8)
	s_mul_i32 s44, s66, 160
	s_add_u32 s100, s98, s44
	s_addc_u32 s101, s99, 0
	global_store_dwordx4 v200, v[26:29], s[100:101] nt
	s_add_u32 s100, s100, s67
	s_addc_u32 s101, s101, 0
	global_store_dwordx4 v200, v[18:21], s[100:101] nt
	v_xor_b32_e32 v226, v201, v226
	v_xor_b32_e32 v227, v201, v227
	v_xor_b32_e32 v228, v201, v228
	v_xor_b32_e32 v229, v201, v229
	v_xor_b32_e32 v230, v201, v230
	v_xor_b32_e32 v231, v201, v231
	v_xor_b32_e32 v232, v201, v232
	v_xor_b32_e32 v233, v201, v233
	s_waitcnt lgkmcnt(4)
	v_mul_f32_e32 v2, v226, v2
	v_fmac_f32_e32 v2, v14, v218
	v_cndmask_b32_e64 v14, v14, v2, s[38:39]
	v_mul_f32_e32 v3, v227, v3
	v_fmac_f32_e32 v3, v15, v219
	v_cndmask_b32_e64 v15, v15, v3, s[38:39]
	v_mul_f32_e32 v4, v228, v4
	v_fmac_f32_e32 v4, v16, v220
	v_cndmask_b32_e64 v16, v16, v4, s[38:39]
	v_mul_f32_e32 v5, v229, v5
	v_fmac_f32_e32 v5, v17, v221
	v_cndmask_b32_e64 v17, v17, v5, s[38:39]
	s_waitcnt lgkmcnt(0)
	v_mul_f32_e32 v162, v230, v162
	v_fmac_f32_e32 v162, v10, v222
	v_cndmask_b32_e64 v10, v10, v162, s[38:39]
	v_mul_f32_e32 v163, v231, v163
	v_fmac_f32_e32 v163, v11, v223
	v_cndmask_b32_e64 v11, v11, v163, s[38:39]
	v_mul_f32_e32 v164, v232, v164
	v_fmac_f32_e32 v164, v12, v224
	v_cndmask_b32_e64 v12, v12, v164, s[38:39]
	v_mul_f32_e32 v165, v233, v165
	v_fmac_f32_e32 v165, v13, v225
	v_cndmask_b32_e64 v13, v13, v165, s[38:39]
	v_pk_mul_f32 v[14:15], v[14:15], s[30:31] op_sel_hi:[1,0]
	v_pk_mul_f32 v[16:17], v[16:17], s[30:31] op_sel_hi:[1,0]
	v_pk_mul_f32 v[10:11], v[10:11], s[30:31] op_sel_hi:[1,0]
	v_pk_mul_f32 v[12:13], v[12:13], s[30:31] op_sel_hi:[1,0]
	v_cvt_pk_bf16_f32 v14, v14, v15
	v_cvt_pk_bf16_f32 v15, v16, v17
	v_cvt_pk_bf16_f32 v16, v10, v11
	v_cvt_pk_bf16_f32 v17, v12, v13
	ds_write_b128 v178, v[14:17]
	ds_write_b128 v178, v[6:9] offset:64
	ds_read_b128 v[10:13], v180
	ds_read_b128 v[2:5], v180 offset:1152
	s_waitcnt lgkmcnt(0)
	s_mul_i32 s44, s66, 176
	s_add_u32 s100, s98, s44
	s_addc_u32 s101, s99, 0
	global_store_dwordx4 v200, v[10:13], s[100:101] nt
	s_add_u32 s100, s100, s67
	s_addc_u32 s101, s101, 0
	global_store_dwordx4 v200, v[2:5], s[100:101] nt
	s_branch .Lipe_done
;     __device__ __forceinline__ void operator()(const f32x4 (&acc)[2][2][4][2], const Unit& u, int wr, int wc, int fr, int fq, PG8_LAS float* stash, int par, PG8_LAS unsigned char* stg, const Unit& un) const {
;     ...
;                 const int row = u.pm * BM + ai * HALF + wr * 64 + m * 16 + fr, pos = row & 4095, b = row >> 12;
;                 const float rs = rsa[ai][m];
; #pragma unroll
;                 for (int bj = 0; bj < 2; ++bj) {
;                     int kind;
;                     if (odd) kind = (u.pn < 6) ? 0 : (u.pn == 6 ? 1 : 2);
;                     else     kind = (u.pn < 2) ? 0 : (u.pn == 2 ? (wc < 2 ? 1 : 2) : 3);
;                     float v[8];
; #pragma unroll
;                     for (int i = 0; i < 4; ++i) { v[i] = acc[ai][bj][m][0][i] * rs; v[4 + i] = acc[ai][bj][m][1][i] * rs; }
;                     if (kind <= 1 && bj == 0) {
;                         const f32x4 c0 = *(const f32x4*)(cs + pos * 16), c1 = *(const f32x4*)(cs + pos * 16 + 4), s0 = *(const f32x4*)(cs + pos * 16 + 8), s1 = *(const f32x4*)(cs + pos * 16 + 12);
; #pragma unroll
;                         for (int i = 0; i < 8; ++i) {
;                             const float c = i < 4 ? c0[i & 3] : c1[i & 3], s = i < 4 ? s0[i & 3] : s1[i & 3];
;                             const float pr = peer_x16(v[i], fq);
;                             const float r = (fq == 0) ? (v[i] * c - pr * s) : (v[i] * c + pr * s);
;                             v[i] = (fq < 2) ? r : v[i];
;                         }
;                     }
;                     if (kind == 0) {
; #pragma unroll
;                         for (int i = 0; i < 8; ++i) v[i] *= C2Q;
;                     }
;                     { u32x4 w; w.x = cvt_pk_bf16(v[0], v[1]); w.y = cvt_pk_bf16(v[2], v[3]); w.z = cvt_pk_bf16(v[4], v[5]); w.w = cvt_pk_bf16(v[6], v[7]);
;                       *(PG8_LAS u32x4*)(stg + fr * 144 + fq * 16 + bj * 64) = w; }
;                 }
;                 {
;                     int kind;
;                     if (odd) kind = (u.pn < 6) ? 0 : (u.pn == 6 ? 1 : 2);
;                     else     kind = (u.pn < 2) ? 0 : (u.pn == 2 ? (wc < 2 ? 1 : 2) : 3);
; #pragma unroll
;                     for (int i = 0; i < 2; ++i) { const int c = fq * 16 + fr + 64 * i, rr = c >> 3, pc = c & 7;
;                         const u32x4 w = *(const PG8_LAS u32x4*)(stg + rr * 144 + pc * 16);
.Lipe_K:
	v_mbcnt_lo_u32_b32 v166, -1, 0
	v_mbcnt_hi_u32_b32 v166, -1, v166
	v_readfirstlane_b32 s65, v180
	v_lshrrev_b32_e32 v167, 2, v166
	v_mul_u32_u24_e32 v167, 0x50, v167
	v_and_b32_e32 v168, 3, v166
	v_lshl_add_u32 v167, v168, 4, v167
	v_add_u32_e32 v167, s65, v167
	v_mul_u32_u24_e32 v168, 0x50, v141
	v_add_u32_e32 v168, s65, v168
	v_lshlrev_b32_e32 v166, 4, v166
	s_add_i32 s44, s19, 0
	s_and_b32 s44, s44, 0xfff
	s_lshl_b32 s44, s44, 6
	s_add_u32 s44, s62, s44
	s_addc_u32 s45, s63, 0
	global_load_dwordx4 v[154:157], v166, s[44:45]
	s_add_i32 s44, s19, 16
	s_and_b32 s44, s44, 0xfff
	s_lshl_b32 s44, s44, 6
	s_add_u32 s44, s62, s44
	s_addc_u32 s45, s63, 0
	global_load_dwordx4 v[158:161], v166, s[44:45]
	s_waitcnt vmcnt(1)
	ds_write_b128 v167, v[154:157]
	ds_read_b128 v[218:221], v168
	ds_read_b128 v[222:225], v168 offset:16
	ds_read_b128 v[226:229], v168 offset:32
	ds_read_b128 v[230:233], v168 offset:48
	v_pk_mul_f32 v[118:119], v[118:119], v[152:153] op_sel_hi:[1,0]
	v_pk_mul_f32 v[120:121], v[120:121], v[152:153] op_sel_hi:[1,0]
	v_pk_mul_f32 v[114:115], v[114:115], v[152:153] op_sel_hi:[1,0]
	v_pk_mul_f32 v[116:117], v[116:117], v[152:153] op_sel_hi:[1,0]
	v_cvt_pk_bf16_f32 v118, v118, v119
	v_cvt_pk_bf16_f32 v119, v120, v121
	v_cvt_pk_bf16_f32 v120, v114, v115
	v_cvt_pk_bf16_f32 v121, v116, v117
	v_pk_mul_f32 v[126:127], v[126:127], v[152:153] op_sel_hi:[1,0]
	v_pk_mul_f32 v[128:129], v[128:129], v[152:153] op_sel_hi:[1,0]
	v_pk_mul_f32 v[122:123], v[122:123], v[152:153] op_sel_hi:[1,0]
	v_pk_mul_f32 v[124:125], v[124:125], v[152:153] op_sel_hi:[1,0]
	ds_swizzle_b32 v114, v126 offset:0x401f
	ds_swizzle_b32 v115, v127 offset:0x401f
	ds_swizzle_b32 v116, v128 offset:0x401f
	ds_swizzle_b32 v117, v129 offset:0x401f
	ds_swizzle_b32 v162, v122 offset:0x401f
	ds_swizzle_b32 v163, v123 offset:0x401f
	ds_swizzle_b32 v164, v124 offset:0x401f
	ds_swizzle_b32 v165, v125 offset:0x401f
	s_waitcnt lgkmcnt(8)
	v_xor_b32_e32 v226, v201, v226
	v_xor_b32_e32 v227, v201, v227
	v_xor_b32_e32 v228, v201, v228
	v_xor_b32_e32 v229, v201, v229
	v_xor_b32_e32 v230, v201, v230
	v_xor_b32_e32 v231, v201, v231
	v_xor_b32_e32 v232, v201, v232
	v_xor_b32_e32 v233, v201, v233
	s_waitcnt lgkmcnt(4)
	v_mul_f32_e32 v114, v226, v114
	v_fmac_f32_e32 v114, v126, v218
	v_cndmask_b32_e64 v126, v126, v114, s[38:39]
	v_mul_f32_e32 v115, v227, v115
	v_fmac_f32_e32 v115, v127, v219
	v_cndmask_b32_e64 v127, v127, v115, s[38:39]
	v_mul_f32_e32 v116, v228, v116
	v_fmac_f32_e32 v116, v128, v220
	v_cndmask_b32_e64 v128, v128, v116, s[38:39]
	v_mul_f32_e32 v117, v229, v117
	v_fmac_f32_e32 v117, v129, v221
	v_cndmask_b32_e64 v129, v129, v117, s[38:39]
	s_waitcnt lgkmcnt(0)
	v_mul_f32_e32 v162, v230, v162
	v_fmac_f32_e32 v162, v122, v222
	v_cndmask_b32_e64 v122, v122, v162, s[38:39]
	v_mul_f32_e32 v163, v231, v163
	v_fmac_f32_e32 v163, v123, v223
	v_cndmask_b32_e64 v123, v123, v163, s[38:39]
	v_mul_f32_e32 v164, v232, v164
	v_fmac_f32_e32 v164, v124, v224
	v_cndmask_b32_e64 v124, v124, v164, s[38:39]
	v_mul_f32_e32 v165, v233, v165
	v_fmac_f32_e32 v165, v125, v225
	v_cndmask_b32_e64 v125, v125, v165, s[38:39]
	v_cvt_pk_bf16_f32 v126, v126, v127
	v_cvt_pk_bf16_f32 v127, v128, v129
	v_cvt_pk_bf16_f32 v128, v122, v123
	v_cvt_pk_bf16_f32 v129, v124, v125
	ds_write_b128 v178, v[126:129]
	ds_write_b128 v178, v[118:121] offset:64
	ds_read_b128 v[122:125], v180
	ds_read_b128 v[114:117], v180 offset:1152
	s_add_i32 s44, s19, 32
	s_and_b32 s44, s44, 0xfff
	s_lshl_b32 s44, s44, 6
	s_add_u32 s44, s62, s44
	s_addc_u32 s45, s63, 0
	global_load_dwordx4 v[154:157], v166, s[44:45]
	s_waitcnt vmcnt(1)
	ds_write_b128 v167, v[158:161]
	ds_read_b128 v[218:221], v168
	ds_read_b128 v[222:225], v168 offset:16
	ds_read_b128 v[226:229], v168 offset:32
	ds_read_b128 v[230:233], v168 offset:48
	v_pk_mul_f32 v[102:103], v[102:103], v[152:153] op_sel:[0,1]
	v_pk_mul_f32 v[104:105], v[104:105], v[152:153] op_sel:[0,1]
	v_pk_mul_f32 v[98:99], v[98:99], v[152:153] op_sel:[0,1]
	v_pk_mul_f32 v[100:101], v[100:101], v[152:153] op_sel:[0,1]
	v_cvt_pk_bf16_f32 v102, v102, v103
	v_cvt_pk_bf16_f32 v103, v104, v105
	v_cvt_pk_bf16_f32 v104, v98, v99
	v_cvt_pk_bf16_f32 v105, v100, v101
	v_pk_mul_f32 v[110:111], v[110:111], v[152:153] op_sel:[0,1]
	v_pk_mul_f32 v[112:113], v[112:113], v[152:153] op_sel:[0,1]
	v_pk_mul_f32 v[106:107], v[106:107], v[152:153] op_sel:[0,1]
	v_pk_mul_f32 v[108:109], v[108:109], v[152:153] op_sel:[0,1]
	ds_swizzle_b32 v98, v110 offset:0x401f
	ds_swizzle_b32 v99, v111 offset:0x401f
	ds_swizzle_b32 v100, v112 offset:0x401f
	ds_swizzle_b32 v101, v113 offset:0x401f
	ds_swizzle_b32 v162, v106 offset:0x401f
	ds_swizzle_b32 v163, v107 offset:0x401f
	ds_swizzle_b32 v164, v108 offset:0x401f
	ds_swizzle_b32 v165, v109 offset:0x401f
	s_waitcnt lgkmcnt(8)
	s_mov_b32 s100, s98
	s_mov_b32 s101, s99
	global_store_dwordx4 v200, v[122:125], s[100:101] nt
	s_add_u32 s100, s100, s67
	s_addc_u32 s101, s101, 0
	global_store_dwordx4 v200, v[114:117], s[100:101] nt
	v_xor_b32_e32 v226, v201, v226
	v_xor_b32_e32 v227, v201, v227
	v_xor_b32_e32 v228, v201, v228
	v_xor_b32_e32 v229, v201, v229
	v_xor_b32_e32 v230, v201, v230
	v_xor_b32_e32 v231, v201, v231
	v_xor_b32_e32 v232, v201, v232
	v_xor_b32_e32 v233, v201, v233
	s_waitcnt lgkmcnt(4)
	v_mul_f32_e32 v98, v226, v98
	v_fmac_f32_e32 v98, v110, v218
	v_cndmask_b32_e64 v110, v110, v98, s[38:39]
	v_mul_f32_e32 v99, v227, v99
	v_fmac_f32_e32 v99, v111, v219
	v_cndmask_b32_e64 v111, v111, v99, s[38:39]
	v_mul_f32_e32 v100, v228, v100
	v_fmac_f32_e32 v100, v112, v220
	v_cndmask_b32_e64 v112, v112, v100, s[38:39]
	v_mul_f32_e32 v101, v229, v101
	v_fmac_f32_e32 v101, v113, v221
	v_cndmask_b32_e64 v113, v113, v101, s[38:39]
	s_waitcnt lgkmcnt(0)
;     __device__ __forceinline__ void operator()(const f32x4 (&acc)[2][2][4][2], const Unit& u, int wr, int wc, int fr, int fq, PG8_LAS float* stash, int par, PG8_LAS unsigned char* stg, const Unit& un) const {
;     ...
;                 const int row = u.pm * BM + ai * HALF + wr * 64 + m * 16 + fr, pos = row & 4095, b = row >> 12;
;                 const float rs = rsa[ai][m];
; #pragma unroll
;                 for (int bj = 0; bj < 2; ++bj) {
;                     int kind;
;                     if (odd) kind = (u.pn < 6) ? 0 : (u.pn == 6 ? 1 : 2);
;                     else     kind = (u.pn < 2) ? 0 : (u.pn == 2 ? (wc < 2 ? 1 : 2) : 3);
;                     float v[8];
; #pragma unroll
;                     for (int i = 0; i < 4; ++i) { v[i] = acc[ai][bj][m][0][i] * rs; v[4 + i] = acc[ai][bj][m][1][i] * rs; }
;                     if (kind <= 1 && bj == 0) {
;                         const f32x4 c0 = *(const f32x4*)(cs + pos * 16), c1 = *(const f32x4*)(cs + pos * 16 + 4), s0 = *(const f32x4*)(cs + pos * 16 + 8), s1 = *(const f32x4*)(cs + pos * 16 + 12);
; #pragma unroll
;                         for (int i = 0; i < 8; ++i) {
;                             const float c = i < 4 ? c0[i & 3] : c1[i & 3], s = i < 4 ? s0[i & 3] : s1[i & 3];
;                             const float pr = peer_x16(v[i], fq);
;                             const float r = (fq == 0) ? (v[i] * c - pr * s) : (v[i] * c + pr * s);
;                             v[i] = (fq < 2) ? r : v[i];
;                         }
;                     }
;                     if (kind == 0) {
; #pragma unroll
;                         for (int i = 0; i < 8; ++i) v[i] *= C2Q;
;                     }
;                     { u32x4 w; w.x = cvt_pk_bf16(v[0], v[1]); w.y = cvt_pk_bf16(v[2], v[3]); w.z = cvt_pk_bf16(v[4], v[5]); w.w = cvt_pk_bf16(v[6], v[7]);
;                       *(PG8_LAS u32x4*)(stg + fr * 144 + fq * 16 + bj * 64) = w; }
;                 }
;                 {
;                     int kind;
;                     if (odd) kind = (u.pn < 6) ? 0 : (u.pn == 6 ? 1 : 2);
;                     else     kind = (u.pn < 2) ? 0 : (u.pn == 2 ? (wc < 2 ? 1 : 2) : 3);
; #pragma unroll
;                     for (int i = 0; i < 2; ++i) { const int c = fq * 16 + fr + 64 * i, rr = c >> 3, pc = c & 7;
;                         const u32x4 w = *(const PG8_LAS u32x4*)(stg + rr * 144 + pc * 16);
	v_mul_f32_e32 v162, v230, v162
	v_fmac_f32_e32 v162, v106, v222
	v_cndmask_b32_e64 v106, v106, v162, s[38:39]
	v_mul_f32_e32 v163, v231, v163
	v_fmac_f32_e32 v163, v107, v223
	v_cndmask_b32_e64 v107, v107, v163, s[38:39]
	v_mul_f32_e32 v164, v232, v164
	v_fmac_f32_e32 v164, v108, v224
	v_cndmask_b32_e64 v108, v108, v164, s[38:39]
	v_mul_f32_e32 v165, v233, v165
	v_fmac_f32_e32 v165, v109, v225
	v_cndmask_b32_e64 v109, v109, v165, s[38:39]
	v_cvt_pk_bf16_f32 v110, v110, v111
	v_cvt_pk_bf16_f32 v111, v112, v113
	v_cvt_pk_bf16_f32 v112, v106, v107
	v_cvt_pk_bf16_f32 v113, v108, v109
	ds_write_b128 v178, v[110:113]
	ds_write_b128 v178, v[102:105] offset:64
	ds_read_b128 v[106:109], v180
	ds_read_b128 v[98:101], v180 offset:1152
	s_add_i32 s44, s19, 48
	s_and_b32 s44, s44, 0xfff
	s_lshl_b32 s44, s44, 6
	s_add_u32 s44, s62, s44
	s_addc_u32 s45, s63, 0
	global_load_dwordx4 v[158:161], v166, s[44:45]
	s_waitcnt vmcnt(3)
	ds_write_b128 v167, v[154:157]
	ds_read_b128 v[218:221], v168
	ds_read_b128 v[222:225], v168 offset:16
	ds_read_b128 v[226:229], v168 offset:32
	ds_read_b128 v[230:233], v168 offset:48
	v_pk_mul_f32 v[86:87], v[86:87], v[150:151] op_sel_hi:[1,0]
	v_pk_mul_f32 v[88:89], v[88:89], v[150:151] op_sel_hi:[1,0]
	v_pk_mul_f32 v[82:83], v[82:83], v[150:151] op_sel_hi:[1,0]
	v_pk_mul_f32 v[84:85], v[84:85], v[150:151] op_sel_hi:[1,0]
	v_cvt_pk_bf16_f32 v86, v86, v87
	v_cvt_pk_bf16_f32 v87, v88, v89
	v_cvt_pk_bf16_f32 v88, v82, v83
	v_cvt_pk_bf16_f32 v89, v84, v85
	v_pk_mul_f32 v[94:95], v[94:95], v[150:151] op_sel_hi:[1,0]
	v_pk_mul_f32 v[96:97], v[96:97], v[150:151] op_sel_hi:[1,0]
	v_pk_mul_f32 v[90:91], v[90:91], v[150:151] op_sel_hi:[1,0]
	v_pk_mul_f32 v[92:93], v[92:93], v[150:151] op_sel_hi:[1,0]
	ds_swizzle_b32 v82, v94 offset:0x401f
	ds_swizzle_b32 v83, v95 offset:0x401f
	ds_swizzle_b32 v84, v96 offset:0x401f
	ds_swizzle_b32 v85, v97 offset:0x401f
	ds_swizzle_b32 v162, v90 offset:0x401f
	ds_swizzle_b32 v163, v91 offset:0x401f
	ds_swizzle_b32 v164, v92 offset:0x401f
	ds_swizzle_b32 v165, v93 offset:0x401f
	s_waitcnt lgkmcnt(8)
	s_mul_i32 s44, s66, 16
	s_add_u32 s100, s98, s44
	s_addc_u32 s101, s99, 0
	global_store_dwordx4 v200, v[106:109], s[100:101] nt
	s_add_u32 s100, s100, s67
	s_addc_u32 s101, s101, 0
	global_store_dwordx4 v200, v[98:101], s[100:101] nt
	v_xor_b32_e32 v226, v201, v226
	v_xor_b32_e32 v227, v201, v227
	v_xor_b32_e32 v228, v201, v228
	v_xor_b32_e32 v229, v201, v229
	v_xor_b32_e32 v230, v201, v230
	v_xor_b32_e32 v231, v201, v231
	v_xor_b32_e32 v232, v201, v232
	v_xor_b32_e32 v233, v201, v233
	s_waitcnt lgkmcnt(4)
	v_mul_f32_e32 v82, v226, v82
	v_fmac_f32_e32 v82, v94, v218
	v_cndmask_b32_e64 v94, v94, v82, s[38:39]
	v_mul_f32_e32 v83, v227, v83
	v_fmac_f32_e32 v83, v95, v219
	v_cndmask_b32_e64 v95, v95, v83, s[38:39]
	v_mul_f32_e32 v84, v228, v84
	v_fmac_f32_e32 v84, v96, v220
	v_cndmask_b32_e64 v96, v96, v84, s[38:39]
	v_mul_f32_e32 v85, v229, v85
	v_fmac_f32_e32 v85, v97, v221
	v_cndmask_b32_e64 v97, v97, v85, s[38:39]
	s_waitcnt lgkmcnt(0)
	v_mul_f32_e32 v162, v230, v162
	v_fmac_f32_e32 v162, v90, v222
	v_cndmask_b32_e64 v90, v90, v162, s[38:39]
	v_mul_f32_e32 v163, v231, v163
	v_fmac_f32_e32 v163, v91, v223
	v_cndmask_b32_e64 v91, v91, v163, s[38:39]
	v_mul_f32_e32 v164, v232, v164
	v_fmac_f32_e32 v164, v92, v224
	v_cndmask_b32_e64 v92, v92, v164, s[38:39]
	v_mul_f32_e32 v165, v233, v165
	v_fmac_f32_e32 v165, v93, v225
	v_cndmask_b32_e64 v93, v93, v165, s[38:39]
	v_cvt_pk_bf16_f32 v94, v94, v95
	v_cvt_pk_bf16_f32 v95, v96, v97
	v_cvt_pk_bf16_f32 v96, v90, v91
	v_cvt_pk_bf16_f32 v97, v92, v93
	ds_write_b128 v178, v[94:97]
	ds_write_b128 v178, v[86:89] offset:64
	ds_read_b128 v[90:93], v180
	ds_read_b128 v[82:85], v180 offset:1152
	s_add_i32 s44, s19, 128
	s_and_b32 s44, s44, 0xfff
	s_lshl_b32 s44, s44, 6
	s_add_u32 s44, s62, s44
	s_addc_u32 s45, s63, 0
	global_load_dwordx4 v[154:157], v166, s[44:45]
	s_waitcnt vmcnt(3)
	ds_write_b128 v167, v[158:161]
	ds_read_b128 v[218:221], v168
	ds_read_b128 v[222:225], v168 offset:16
	ds_read_b128 v[226:229], v168 offset:32
	ds_read_b128 v[230:233], v168 offset:48
	v_pk_mul_f32 v[70:71], v[70:71], v[150:151] op_sel:[0,1]
	v_pk_mul_f32 v[72:73], v[72:73], v[150:151] op_sel:[0,1]
	v_pk_mul_f32 v[66:67], v[66:67], v[150:151] op_sel:[0,1]
	v_pk_mul_f32 v[68:69], v[68:69], v[150:151] op_sel:[0,1]
	v_cvt_pk_bf16_f32 v70, v70, v71
	v_cvt_pk_bf16_f32 v71, v72, v73
	v_cvt_pk_bf16_f32 v72, v66, v67
	v_cvt_pk_bf16_f32 v73, v68, v69
	v_pk_mul_f32 v[78:79], v[78:79], v[150:151] op_sel:[0,1]
	v_pk_mul_f32 v[80:81], v[80:81], v[150:151] op_sel:[0,1]
	v_pk_mul_f32 v[74:75], v[74:75], v[150:151] op_sel:[0,1]
	v_pk_mul_f32 v[76:77], v[76:77], v[150:151] op_sel:[0,1]
	ds_swizzle_b32 v66, v78 offset:0x401f
	ds_swizzle_b32 v67, v79 offset:0x401f
	ds_swizzle_b32 v68, v80 offset:0x401f
	ds_swizzle_b32 v69, v81 offset:0x401f
	ds_swizzle_b32 v162, v74 offset:0x401f
	ds_swizzle_b32 v163, v75 offset:0x401f
	ds_swizzle_b32 v164, v76 offset:0x401f
	ds_swizzle_b32 v165, v77 offset:0x401f
	s_waitcnt lgkmcnt(8)
	s_mul_i32 s44, s66, 32
	s_add_u32 s100, s98, s44
	s_addc_u32 s101, s99, 0
	global_store_dwordx4 v200, v[90:93], s[100:101] nt
	s_add_u32 s100, s100, s67
	s_addc_u32 s101, s101, 0
	global_store_dwordx4 v200, v[82:85], s[100:101] nt
	v_xor_b32_e32 v226, v201, v226
	v_xor_b32_e32 v227, v201, v227
	v_xor_b32_e32 v228, v201, v228
	v_xor_b32_e32 v229, v201, v229
	v_xor_b32_e32 v230, v201, v230
	v_xor_b32_e32 v231, v201, v231
	v_xor_b32_e32 v232, v201, v232
	v_xor_b32_e32 v233, v201, v233
	s_waitcnt lgkmcnt(4)
;     __device__ __forceinline__ void operator()(const f32x4 (&acc)[2][2][4][2], const Unit& u, int wr, int wc, int fr, int fq, PG8_LAS float* stash, int par, PG8_LAS unsigned char* stg, const Unit& un) const {
;     ...
;                 const int row = u.pm * BM + ai * HALF + wr * 64 + m * 16 + fr, pos = row & 4095, b = row >> 12;
;                 const float rs = rsa[ai][m];
; #pragma unroll
;                 for (int bj = 0; bj < 2; ++bj) {
;                     int kind;
;                     if (odd) kind = (u.pn < 6) ? 0 : (u.pn == 6 ? 1 : 2);
;                     else     kind = (u.pn < 2) ? 0 : (u.pn == 2 ? (wc < 2 ? 1 : 2) : 3);
;                     float v[8];
; #pragma unroll
;                     for (int i = 0; i < 4; ++i) { v[i] = acc[ai][bj][m][0][i] * rs; v[4 + i] = acc[ai][bj][m][1][i] * rs; }
;                     if (kind <= 1 && bj == 0) {
;                         const f32x4 c0 = *(const f32x4*)(cs + pos * 16), c1 = *(const f32x4*)(cs + pos * 16 + 4), s0 = *(const f32x4*)(cs + pos * 16 + 8), s1 = *(const f32x4*)(cs + pos * 16 + 12);
; #pragma unroll
;                         for (int i = 0; i < 8; ++i) {
;                             const float c = i < 4 ? c0[i & 3] : c1[i & 3], s = i < 4 ? s0[i & 3] : s1[i & 3];
;                             const float pr = peer_x16(v[i], fq);
;                             const float r = (fq == 0) ? (v[i] * c - pr * s) : (v[i] * c + pr * s);
;                             v[i] = (fq < 2) ? r : v[i];
;                         }
;                     }
;                     if (kind == 0) {
; #pragma unroll
;                         for (int i = 0; i < 8; ++i) v[i] *= C2Q;
;                     }
;                     { u32x4 w; w.x = cvt_pk_bf16(v[0], v[1]); w.y = cvt_pk_bf16(v[2], v[3]); w.z = cvt_pk_bf16(v[4], v[5]); w.w = cvt_pk_bf16(v[6], v[7]);
;                       *(PG8_LAS u32x4*)(stg + fr * 144 + fq * 16 + bj * 64) = w; }
;                 }
;                 {
;                     int kind;
;                     if (odd) kind = (u.pn < 6) ? 0 : (u.pn == 6 ? 1 : 2);
;                     else     kind = (u.pn < 2) ? 0 : (u.pn == 2 ? (wc < 2 ? 1 : 2) : 3);
; #pragma unroll
;                     for (int i = 0; i < 2; ++i) { const int c = fq * 16 + fr + 64 * i, rr = c >> 3, pc = c & 7;
;                         const u32x4 w = *(const PG8_LAS u32x4*)(stg + rr * 144 + pc * 16);
	v_mul_f32_e32 v66, v226, v66
	v_fmac_f32_e32 v66, v78, v218
	v_cndmask_b32_e64 v78, v78, v66, s[38:39]
	v_mul_f32_e32 v67, v227, v67
	v_fmac_f32_e32 v67, v79, v219
	v_cndmask_b32_e64 v79, v79, v67, s[38:39]
	v_mul_f32_e32 v68, v228, v68
	v_fmac_f32_e32 v68, v80, v220
	v_cndmask_b32_e64 v80, v80, v68, s[38:39]
	v_mul_f32_e32 v69, v229, v69
	v_fmac_f32_e32 v69, v81, v221
	v_cndmask_b32_e64 v81, v81, v69, s[38:39]
	s_waitcnt lgkmcnt(0)
	v_mul_f32_e32 v162, v230, v162
	v_fmac_f32_e32 v162, v74, v222
	v_cndmask_b32_e64 v74, v74, v162, s[38:39]
	v_mul_f32_e32 v163, v231, v163
	v_fmac_f32_e32 v163, v75, v223
	v_cndmask_b32_e64 v75, v75, v163, s[38:39]
	v_mul_f32_e32 v164, v232, v164
	v_fmac_f32_e32 v164, v76, v224
	v_cndmask_b32_e64 v76, v76, v164, s[38:39]
	v_mul_f32_e32 v165, v233, v165
	v_fmac_f32_e32 v165, v77, v225
	v_cndmask_b32_e64 v77, v77, v165, s[38:39]
	v_cvt_pk_bf16_f32 v78, v78, v79
	v_cvt_pk_bf16_f32 v79, v80, v81
	v_cvt_pk_bf16_f32 v80, v74, v75
	v_cvt_pk_bf16_f32 v81, v76, v77
	ds_write_b128 v178, v[78:81]
	ds_write_b128 v178, v[70:73] offset:64
	ds_read_b128 v[74:77], v180
	ds_read_b128 v[66:69], v180 offset:1152
	s_add_i32 s44, s19, 144
	s_and_b32 s44, s44, 0xfff
	s_lshl_b32 s44, s44, 6
	s_add_u32 s44, s62, s44
	s_addc_u32 s45, s63, 0
	global_load_dwordx4 v[158:161], v166, s[44:45]
	s_waitcnt vmcnt(3)
	ds_write_b128 v167, v[154:157]
	ds_read_b128 v[218:221], v168
	ds_read_b128 v[222:225], v168 offset:16
	ds_read_b128 v[226:229], v168 offset:32
	ds_read_b128 v[230:233], v168 offset:48
	v_pk_mul_f32 v[54:55], v[54:55], v[148:149] op_sel_hi:[1,0]
	v_pk_mul_f32 v[56:57], v[56:57], v[148:149] op_sel_hi:[1,0]
	v_pk_mul_f32 v[50:51], v[50:51], v[148:149] op_sel_hi:[1,0]
	v_pk_mul_f32 v[52:53], v[52:53], v[148:149] op_sel_hi:[1,0]
	v_cvt_pk_bf16_f32 v54, v54, v55
	v_cvt_pk_bf16_f32 v55, v56, v57
	v_cvt_pk_bf16_f32 v56, v50, v51
	v_cvt_pk_bf16_f32 v57, v52, v53
	v_pk_mul_f32 v[62:63], v[62:63], v[148:149] op_sel_hi:[1,0]
	v_pk_mul_f32 v[64:65], v[64:65], v[148:149] op_sel_hi:[1,0]
	v_pk_mul_f32 v[58:59], v[58:59], v[148:149] op_sel_hi:[1,0]
	v_pk_mul_f32 v[60:61], v[60:61], v[148:149] op_sel_hi:[1,0]
	ds_swizzle_b32 v50, v62 offset:0x401f
	ds_swizzle_b32 v51, v63 offset:0x401f
	ds_swizzle_b32 v52, v64 offset:0x401f
	ds_swizzle_b32 v53, v65 offset:0x401f
	ds_swizzle_b32 v162, v58 offset:0x401f
	ds_swizzle_b32 v163, v59 offset:0x401f
	ds_swizzle_b32 v164, v60 offset:0x401f
	ds_swizzle_b32 v165, v61 offset:0x401f
	s_waitcnt lgkmcnt(8)
	s_mul_i32 s44, s66, 48
	s_add_u32 s100, s98, s44
	s_addc_u32 s101, s99, 0
	global_store_dwordx4 v200, v[74:77], s[100:101] nt
	s_add_u32 s100, s100, s67
	s_addc_u32 s101, s101, 0
	global_store_dwordx4 v200, v[66:69], s[100:101] nt
	v_xor_b32_e32 v226, v201, v226
	v_xor_b32_e32 v227, v201, v227
	v_xor_b32_e32 v228, v201, v228
	v_xor_b32_e32 v229, v201, v229
	v_xor_b32_e32 v230, v201, v230
	v_xor_b32_e32 v231, v201, v231
	v_xor_b32_e32 v232, v201, v232
	v_xor_b32_e32 v233, v201, v233
	s_waitcnt lgkmcnt(4)
	v_mul_f32_e32 v50, v226, v50
	v_fmac_f32_e32 v50, v62, v218
	v_cndmask_b32_e64 v62, v62, v50, s[38:39]
	v_mul_f32_e32 v51, v227, v51
	v_fmac_f32_e32 v51, v63, v219
	v_cndmask_b32_e64 v63, v63, v51, s[38:39]
	v_mul_f32_e32 v52, v228, v52
	v_fmac_f32_e32 v52, v64, v220
	v_cndmask_b32_e64 v64, v64, v52, s[38:39]
	v_mul_f32_e32 v53, v229, v53
	v_fmac_f32_e32 v53, v65, v221
	v_cndmask_b32_e64 v65, v65, v53, s[38:39]
	s_waitcnt lgkmcnt(0)
	v_mul_f32_e32 v162, v230, v162
	v_fmac_f32_e32 v162, v58, v222
	v_cndmask_b32_e64 v58, v58, v162, s[38:39]
	v_mul_f32_e32 v163, v231, v163
	v_fmac_f32_e32 v163, v59, v223
	v_cndmask_b32_e64 v59, v59, v163, s[38:39]
	v_mul_f32_e32 v164, v232, v164
	v_fmac_f32_e32 v164, v60, v224
	v_cndmask_b32_e64 v60, v60, v164, s[38:39]
	v_mul_f32_e32 v165, v233, v165
	v_fmac_f32_e32 v165, v61, v225
	v_cndmask_b32_e64 v61, v61, v165, s[38:39]
	v_cvt_pk_bf16_f32 v62, v62, v63
	v_cvt_pk_bf16_f32 v63, v64, v65
	v_cvt_pk_bf16_f32 v64, v58, v59
	v_cvt_pk_bf16_f32 v65, v60, v61
	ds_write_b128 v178, v[62:65]
	ds_write_b128 v178, v[54:57] offset:64
	ds_read_b128 v[58:61], v180
	ds_read_b128 v[50:53], v180 offset:1152
	s_add_i32 s44, s19, 160
	s_and_b32 s44, s44, 0xfff
	s_lshl_b32 s44, s44, 6
	s_add_u32 s44, s62, s44
	s_addc_u32 s45, s63, 0
	global_load_dwordx4 v[154:157], v166, s[44:45]
	s_waitcnt vmcnt(3)
	ds_write_b128 v167, v[158:161]
	ds_read_b128 v[218:221], v168
	ds_read_b128 v[222:225], v168 offset:16
	ds_read_b128 v[226:229], v168 offset:32
	ds_read_b128 v[230:233], v168 offset:48
	v_pk_mul_f32 v[38:39], v[38:39], v[148:149] op_sel:[0,1]
	v_pk_mul_f32 v[40:41], v[40:41], v[148:149] op_sel:[0,1]
	v_pk_mul_f32 v[34:35], v[34:35], v[148:149] op_sel:[0,1]
	v_pk_mul_f32 v[36:37], v[36:37], v[148:149] op_sel:[0,1]
	v_cvt_pk_bf16_f32 v38, v38, v39
	v_cvt_pk_bf16_f32 v39, v40, v41
	v_cvt_pk_bf16_f32 v40, v34, v35
	v_cvt_pk_bf16_f32 v41, v36, v37
	v_pk_mul_f32 v[46:47], v[46:47], v[148:149] op_sel:[0,1]
	v_pk_mul_f32 v[48:49], v[48:49], v[148:149] op_sel:[0,1]
	v_pk_mul_f32 v[42:43], v[42:43], v[148:149] op_sel:[0,1]
	v_pk_mul_f32 v[44:45], v[44:45], v[148:149] op_sel:[0,1]
	ds_swizzle_b32 v34, v46 offset:0x401f
	ds_swizzle_b32 v35, v47 offset:0x401f
	ds_swizzle_b32 v36, v48 offset:0x401f
	ds_swizzle_b32 v37, v49 offset:0x401f
	ds_swizzle_b32 v162, v42 offset:0x401f
	ds_swizzle_b32 v163, v43 offset:0x401f
	ds_swizzle_b32 v164, v44 offset:0x401f
	ds_swizzle_b32 v165, v45 offset:0x401f
	s_waitcnt lgkmcnt(8)
;     __device__ __forceinline__ void operator()(const f32x4 (&acc)[2][2][4][2], const Unit& u, int wr, int wc, int fr, int fq, PG8_LAS float* stash, int par, PG8_LAS unsigned char* stg, const Unit& un) const {
;     ...
;                 const int row = u.pm * BM + ai * HALF + wr * 64 + m * 16 + fr, pos = row & 4095, b = row >> 12;
;                 const float rs = rsa[ai][m];
; #pragma unroll
;                 for (int bj = 0; bj < 2; ++bj) {
;                     int kind;
;                     if (odd) kind = (u.pn < 6) ? 0 : (u.pn == 6 ? 1 : 2);
;                     else     kind = (u.pn < 2) ? 0 : (u.pn == 2 ? (wc < 2 ? 1 : 2) : 3);
;                     float v[8];
; #pragma unroll
;                     for (int i = 0; i < 4; ++i) { v[i] = acc[ai][bj][m][0][i] * rs; v[4 + i] = acc[ai][bj][m][1][i] * rs; }
;                     if (kind <= 1 && bj == 0) {
;                         const f32x4 c0 = *(const f32x4*)(cs + pos * 16), c1 = *(const f32x4*)(cs + pos * 16 + 4), s0 = *(const f32x4*)(cs + pos * 16 + 8), s1 = *(const f32x4*)(cs + pos * 16 + 12);
; #pragma unroll
;                         for (int i = 0; i < 8; ++i) {
;                             const float c = i < 4 ? c0[i & 3] : c1[i & 3], s = i < 4 ? s0[i & 3] : s1[i & 3];
;                             const float pr = peer_x16(v[i], fq);
;                             const float r = (fq == 0) ? (v[i] * c - pr * s) : (v[i] * c + pr * s);
;                             v[i] = (fq < 2) ? r : v[i];
;                         }
;                     }
;                     if (kind == 0) {
; #pragma unroll
;                         for (int i = 0; i < 8; ++i) v[i] *= C2Q;
;                     }
;                     { u32x4 w; w.x = cvt_pk_bf16(v[0], v[1]); w.y = cvt_pk_bf16(v[2], v[3]); w.z = cvt_pk_bf16(v[4], v[5]); w.w = cvt_pk_bf16(v[6], v[7]);
;                       *(PG8_LAS u32x4*)(stg + fr * 144 + fq * 16 + bj * 64) = w; }
;                 }
;                 {
;                     int kind;
;                     if (odd) kind = (u.pn < 6) ? 0 : (u.pn == 6 ? 1 : 2);
;                     else     kind = (u.pn < 2) ? 0 : (u.pn == 2 ? (wc < 2 ? 1 : 2) : 3);
; #pragma unroll
;                     for (int i = 0; i < 2; ++i) { const int c = fq * 16 + fr + 64 * i, rr = c >> 3, pc = c & 7;
;                         const u32x4 w = *(const PG8_LAS u32x4*)(stg + rr * 144 + pc * 16);
	s_mul_i32 s44, s66, 128
	s_add_u32 s100, s98, s44
	s_addc_u32 s101, s99, 0
	global_store_dwordx4 v200, v[58:61], s[100:101] nt
	s_add_u32 s100, s100, s67
	s_addc_u32 s101, s101, 0
	global_store_dwordx4 v200, v[50:53], s[100:101] nt
	v_xor_b32_e32 v226, v201, v226
	v_xor_b32_e32 v227, v201, v227
	v_xor_b32_e32 v228, v201, v228
	v_xor_b32_e32 v229, v201, v229
	v_xor_b32_e32 v230, v201, v230
	v_xor_b32_e32 v231, v201, v231
	v_xor_b32_e32 v232, v201, v232
	v_xor_b32_e32 v233, v201, v233
	s_waitcnt lgkmcnt(4)
	v_mul_f32_e32 v34, v226, v34
	v_fmac_f32_e32 v34, v46, v218
	v_cndmask_b32_e64 v46, v46, v34, s[38:39]
	v_mul_f32_e32 v35, v227, v35
	v_fmac_f32_e32 v35, v47, v219
	v_cndmask_b32_e64 v47, v47, v35, s[38:39]
	v_mul_f32_e32 v36, v228, v36
	v_fmac_f32_e32 v36, v48, v220
	v_cndmask_b32_e64 v48, v48, v36, s[38:39]
	v_mul_f32_e32 v37, v229, v37
	v_fmac_f32_e32 v37, v49, v221
	v_cndmask_b32_e64 v49, v49, v37, s[38:39]
	s_waitcnt lgkmcnt(0)
	v_mul_f32_e32 v162, v230, v162
	v_fmac_f32_e32 v162, v42, v222
	v_cndmask_b32_e64 v42, v42, v162, s[38:39]
	v_mul_f32_e32 v163, v231, v163
	v_fmac_f32_e32 v163, v43, v223
	v_cndmask_b32_e64 v43, v43, v163, s[38:39]
	v_mul_f32_e32 v164, v232, v164
	v_fmac_f32_e32 v164, v44, v224
	v_cndmask_b32_e64 v44, v44, v164, s[38:39]
	v_mul_f32_e32 v165, v233, v165
	v_fmac_f32_e32 v165, v45, v225
	v_cndmask_b32_e64 v45, v45, v165, s[38:39]
	v_cvt_pk_bf16_f32 v46, v46, v47
	v_cvt_pk_bf16_f32 v47, v48, v49
	v_cvt_pk_bf16_f32 v48, v42, v43
	v_cvt_pk_bf16_f32 v49, v44, v45
	ds_write_b128 v178, v[46:49]
	ds_write_b128 v178, v[38:41] offset:64
	ds_read_b128 v[42:45], v180
	ds_read_b128 v[34:37], v180 offset:1152
	s_add_i32 s44, s19, 176
	s_and_b32 s44, s44, 0xfff
	s_lshl_b32 s44, s44, 6
	s_add_u32 s44, s62, s44
	s_addc_u32 s45, s63, 0
	global_load_dwordx4 v[158:161], v166, s[44:45]
	s_waitcnt vmcnt(3)
	ds_write_b128 v167, v[154:157]
	ds_read_b128 v[218:221], v168
	ds_read_b128 v[222:225], v168 offset:16
	ds_read_b128 v[226:229], v168 offset:32
	ds_read_b128 v[230:233], v168 offset:48
	v_pk_mul_f32 v[22:23], v[22:23], v[146:147] op_sel_hi:[1,0]
	v_pk_mul_f32 v[24:25], v[24:25], v[146:147] op_sel_hi:[1,0]
	v_pk_mul_f32 v[18:19], v[18:19], v[146:147] op_sel_hi:[1,0]
	v_pk_mul_f32 v[20:21], v[20:21], v[146:147] op_sel_hi:[1,0]
	v_cvt_pk_bf16_f32 v22, v22, v23
	v_cvt_pk_bf16_f32 v23, v24, v25
	v_cvt_pk_bf16_f32 v24, v18, v19
	v_cvt_pk_bf16_f32 v25, v20, v21
	v_pk_mul_f32 v[30:31], v[30:31], v[146:147] op_sel_hi:[1,0]
	v_pk_mul_f32 v[32:33], v[32:33], v[146:147] op_sel_hi:[1,0]
	v_pk_mul_f32 v[26:27], v[26:27], v[146:147] op_sel_hi:[1,0]
	v_pk_mul_f32 v[28:29], v[28:29], v[146:147] op_sel_hi:[1,0]
	ds_swizzle_b32 v18, v30 offset:0x401f
	ds_swizzle_b32 v19, v31 offset:0x401f
	ds_swizzle_b32 v20, v32 offset:0x401f
	ds_swizzle_b32 v21, v33 offset:0x401f
	ds_swizzle_b32 v162, v26 offset:0x401f
	ds_swizzle_b32 v163, v27 offset:0x401f
	ds_swizzle_b32 v164, v28 offset:0x401f
	ds_swizzle_b32 v165, v29 offset:0x401f
	s_waitcnt lgkmcnt(8)
	s_mul_i32 s44, s66, 144
	s_add_u32 s100, s98, s44
	s_addc_u32 s101, s99, 0
	global_store_dwordx4 v200, v[42:45], s[100:101] nt
	s_add_u32 s100, s100, s67
	s_addc_u32 s101, s101, 0
	global_store_dwordx4 v200, v[34:37], s[100:101] nt
	v_xor_b32_e32 v226, v201, v226
	v_xor_b32_e32 v227, v201, v227
	v_xor_b32_e32 v228, v201, v228
	v_xor_b32_e32 v229, v201, v229
	v_xor_b32_e32 v230, v201, v230
	v_xor_b32_e32 v231, v201, v231
	v_xor_b32_e32 v232, v201, v232
	v_xor_b32_e32 v233, v201, v233
	s_waitcnt lgkmcnt(4)
	v_mul_f32_e32 v18, v226, v18
	v_fmac_f32_e32 v18, v30, v218
	v_cndmask_b32_e64 v30, v30, v18, s[38:39]
	v_mul_f32_e32 v19, v227, v19
	v_fmac_f32_e32 v19, v31, v219
	v_cndmask_b32_e64 v31, v31, v19, s[38:39]
	v_mul_f32_e32 v20, v228, v20
	v_fmac_f32_e32 v20, v32, v220
	v_cndmask_b32_e64 v32, v32, v20, s[38:39]
	v_mul_f32_e32 v21, v229, v21
	v_fmac_f32_e32 v21, v33, v221
	v_cndmask_b32_e64 v33, v33, v21, s[38:39]
	s_waitcnt lgkmcnt(0)
;     __device__ __forceinline__ void operator()(const f32x4 (&acc)[2][2][4][2], const Unit& u, int wr, int wc, int fr, int fq, PG8_LAS float* stash, int par, PG8_LAS unsigned char* stg, const Unit& un) const {
;     ...
;                 const int row = u.pm * BM + ai * HALF + wr * 64 + m * 16 + fr, pos = row & 4095, b = row >> 12;
;                 const float rs = rsa[ai][m];
; #pragma unroll
;                 for (int bj = 0; bj < 2; ++bj) {
;                     int kind;
;                     if (odd) kind = (u.pn < 6) ? 0 : (u.pn == 6 ? 1 : 2);
;                     else     kind = (u.pn < 2) ? 0 : (u.pn == 2 ? (wc < 2 ? 1 : 2) : 3);
;                     float v[8];
; #pragma unroll
;                     for (int i = 0; i < 4; ++i) { v[i] = acc[ai][bj][m][0][i] * rs; v[4 + i] = acc[ai][bj][m][1][i] * rs; }
;                     if (kind <= 1 && bj == 0) {
;                         const f32x4 c0 = *(const f32x4*)(cs + pos * 16), c1 = *(const f32x4*)(cs + pos * 16 + 4), s0 = *(const f32x4*)(cs + pos * 16 + 8), s1 = *(const f32x4*)(cs + pos * 16 + 12);
; #pragma unroll
;                         for (int i = 0; i < 8; ++i) {
;                             const float c = i < 4 ? c0[i & 3] : c1[i & 3], s = i < 4 ? s0[i & 3] : s1[i & 3];
;                             const float pr = peer_x16(v[i], fq);
;                             const float r = (fq == 0) ? (v[i] * c - pr * s) : (v[i] * c + pr * s);
;                             v[i] = (fq < 2) ? r : v[i];
;                         }
;                     }
;                     if (kind == 0) {
; #pragma unroll
;                         for (int i = 0; i < 8; ++i) v[i] *= C2Q;
;                     }
;                     { u32x4 w; w.x = cvt_pk_bf16(v[0], v[1]); w.y = cvt_pk_bf16(v[2], v[3]); w.z = cvt_pk_bf16(v[4], v[5]); w.w = cvt_pk_bf16(v[6], v[7]);
;                       *(PG8_LAS u32x4*)(stg + fr * 144 + fq * 16 + bj * 64) = w; }
;                 }
;                 {
;                     int kind;
;                     if (odd) kind = (u.pn < 6) ? 0 : (u.pn == 6 ? 1 : 2);
;                     else     kind = (u.pn < 2) ? 0 : (u.pn == 2 ? (wc < 2 ? 1 : 2) : 3);
; #pragma unroll
;                     for (int i = 0; i < 2; ++i) { const int c = fq * 16 + fr + 64 * i, rr = c >> 3, pc = c & 7;
;                         const u32x4 w = *(const PG8_LAS u32x4*)(stg + rr * 144 + pc * 16);
	v_mul_f32_e32 v162, v230, v162
	v_fmac_f32_e32 v162, v26, v222
	v_cndmask_b32_e64 v26, v26, v162, s[38:39]
	v_mul_f32_e32 v163, v231, v163
	v_fmac_f32_e32 v163, v27, v223
	v_cndmask_b32_e64 v27, v27, v163, s[38:39]
	v_mul_f32_e32 v164, v232, v164
	v_fmac_f32_e32 v164, v28, v224
	v_cndmask_b32_e64 v28, v28, v164, s[38:39]
	v_mul_f32_e32 v165, v233, v165
	v_fmac_f32_e32 v165, v29, v225
	v_cndmask_b32_e64 v29, v29, v165, s[38:39]
	v_cvt_pk_bf16_f32 v30, v30, v31
	v_cvt_pk_bf16_f32 v31, v32, v33
	v_cvt_pk_bf16_f32 v32, v26, v27
	v_cvt_pk_bf16_f32 v33, v28, v29
	ds_write_b128 v178, v[30:33]
	ds_write_b128 v178, v[22:25] offset:64
	ds_read_b128 v[26:29], v180
	ds_read_b128 v[18:21], v180 offset:1152
	s_waitcnt vmcnt(2)
	ds_write_b128 v167, v[158:161]
	ds_read_b128 v[218:221], v168
	ds_read_b128 v[222:225], v168 offset:16
	ds_read_b128 v[226:229], v168 offset:32
	ds_read_b128 v[230:233], v168 offset:48
	v_pk_mul_f32 v[6:7], v[6:7], v[146:147] op_sel:[0,1]
	v_pk_mul_f32 v[8:9], v[8:9], v[146:147] op_sel:[0,1]
	v_pk_mul_f32 v[2:3], v[2:3], v[146:147] op_sel:[0,1]
	v_pk_mul_f32 v[4:5], v[4:5], v[146:147] op_sel:[0,1]
	v_cvt_pk_bf16_f32 v6, v6, v7
	v_cvt_pk_bf16_f32 v7, v8, v9
	v_cvt_pk_bf16_f32 v8, v2, v3
	v_cvt_pk_bf16_f32 v9, v4, v5
	v_pk_mul_f32 v[14:15], v[14:15], v[146:147] op_sel:[0,1]
	v_pk_mul_f32 v[16:17], v[16:17], v[146:147] op_sel:[0,1]
	v_pk_mul_f32 v[10:11], v[10:11], v[146:147] op_sel:[0,1]
	v_pk_mul_f32 v[12:13], v[12:13], v[146:147] op_sel:[0,1]
	ds_swizzle_b32 v2, v14 offset:0x401f
	ds_swizzle_b32 v3, v15 offset:0x401f
	ds_swizzle_b32 v4, v16 offset:0x401f
	ds_swizzle_b32 v5, v17 offset:0x401f
	ds_swizzle_b32 v162, v10 offset:0x401f
	ds_swizzle_b32 v163, v11 offset:0x401f
	ds_swizzle_b32 v164, v12 offset:0x401f
	ds_swizzle_b32 v165, v13 offset:0x401f
	s_waitcnt lgkmcnt(8)
	s_mul_i32 s44, s66, 160
	s_add_u32 s100, s98, s44
	s_addc_u32 s101, s99, 0
	global_store_dwordx4 v200, v[26:29], s[100:101] nt
	s_add_u32 s100, s100, s67
	s_addc_u32 s101, s101, 0
	global_store_dwordx4 v200, v[18:21], s[100:101] nt
	v_xor_b32_e32 v226, v201, v226
	v_xor_b32_e32 v227, v201, v227
	v_xor_b32_e32 v228, v201, v228
	v_xor_b32_e32 v229, v201, v229
	v_xor_b32_e32 v230, v201, v230
	v_xor_b32_e32 v231, v201, v231
	v_xor_b32_e32 v232, v201, v232
	v_xor_b32_e32 v233, v201, v233
	s_waitcnt lgkmcnt(4)
	v_mul_f32_e32 v2, v226, v2
	v_fmac_f32_e32 v2, v14, v218
	v_cndmask_b32_e64 v14, v14, v2, s[38:39]
	v_mul_f32_e32 v3, v227, v3
	v_fmac_f32_e32 v3, v15, v219
	v_cndmask_b32_e64 v15, v15, v3, s[38:39]
	v_mul_f32_e32 v4, v228, v4
	v_fmac_f32_e32 v4, v16, v220
	v_cndmask_b32_e64 v16, v16, v4, s[38:39]
	v_mul_f32_e32 v5, v229, v5
	v_fmac_f32_e32 v5, v17, v221
	v_cndmask_b32_e64 v17, v17, v5, s[38:39]
	s_waitcnt lgkmcnt(0)
	v_mul_f32_e32 v162, v230, v162
	v_fmac_f32_e32 v162, v10, v222
	v_cndmask_b32_e64 v10, v10, v162, s[38:39]
	v_mul_f32_e32 v163, v231, v163
	v_fmac_f32_e32 v163, v11, v223
	v_cndmask_b32_e64 v11, v11, v163, s[38:39]
	v_mul_f32_e32 v164, v232, v164
	v_fmac_f32_e32 v164, v12, v224
	v_cndmask_b32_e64 v12, v12, v164, s[38:39]
	v_mul_f32_e32 v165, v233, v165
	v_fmac_f32_e32 v165, v13, v225
	v_cndmask_b32_e64 v13, v13, v165, s[38:39]
	v_cvt_pk_bf16_f32 v14, v14, v15
	v_cvt_pk_bf16_f32 v15, v16, v17
	v_cvt_pk_bf16_f32 v16, v10, v11
	v_cvt_pk_bf16_f32 v17, v12, v13
	ds_write_b128 v178, v[14:17]
	ds_write_b128 v178, v[6:9] offset:64
	ds_read_b128 v[10:13], v180
	ds_read_b128 v[2:5], v180 offset:1152
	s_waitcnt lgkmcnt(0)
	s_mul_i32 s44, s66, 176
	s_add_u32 s100, s98, s44
	s_addc_u32 s101, s99, 0
	global_store_dwordx4 v200, v[10:13], s[100:101] nt
	s_add_u32 s100, s100, s67
	s_addc_u32 s101, s101, 0
	global_store_dwordx4 v200, v[2:5], s[100:101] nt
	s_branch .Lipe_done
